# GEMM accumulator clearing with 64 v_mov_b64 instead of 128 v_mov_b32 per tile; counted vmcnt waits for the x rows in the gate epilogue
# speedup vs baseline: 1.0161x; 1.0048x over previous
; template <class Epi, class S_t>
; __device__ __forceinline__ void gemm_phase(LAS unsigned char* lds, int lda, int ldb, const S_t& S, const Epi& E) {
;     ...
; #pragma unroll
;         for (int a = 0; a < 2; ++a)
; #pragma unroll
;             for (int b = 0; b < 2; ++b)
; #pragma unroll
;                 for (int m = 0; m < 4; ++m)
; #pragma unroll
;                     for (int n = 0; n < 2; ++n) acc[a][b][m][n] = (f32x4){0.f, 0.f, 0.f, 0.f};
.LBB0_132:
	s_add_u32 s16, s16, 0x80080
	s_addc_u32 s17, s17, 0
	s_add_u32 s0, s18, 0x100
	s_addc_u32 s1, s19, 0
	s_mov_b32 s9, -2
	v_mov_b64_e32 v[0:1], 0
	v_mov_b64_e32 v[2:3], 0
	v_mov_b64_e32 v[4:5], 0
	v_mov_b64_e32 v[6:7], 0
	v_mov_b64_e32 v[8:9], 0
	v_mov_b64_e32 v[10:11], 0
	v_mov_b64_e32 v[12:13], 0
	v_mov_b64_e32 v[14:15], 0
	v_mov_b64_e32 v[16:17], 0
	v_mov_b64_e32 v[18:19], 0
	v_mov_b64_e32 v[20:21], 0
	v_mov_b64_e32 v[22:23], 0
	v_mov_b64_e32 v[24:25], 0
	v_mov_b64_e32 v[26:27], 0
	v_mov_b64_e32 v[28:29], 0
	v_mov_b64_e32 v[30:31], 0
	v_mov_b64_e32 v[32:33], 0
	v_mov_b64_e32 v[34:35], 0
	v_mov_b64_e32 v[36:37], 0
	v_mov_b64_e32 v[38:39], 0
	v_mov_b64_e32 v[40:41], 0
	v_mov_b64_e32 v[42:43], 0
	v_mov_b64_e32 v[44:45], 0
	v_mov_b64_e32 v[46:47], 0
	v_mov_b64_e32 v[48:49], 0
	v_mov_b64_e32 v[50:51], 0
	v_mov_b64_e32 v[52:53], 0
	v_mov_b64_e32 v[54:55], 0
	v_mov_b64_e32 v[56:57], 0
	v_mov_b64_e32 v[58:59], 0
	v_mov_b64_e32 v[60:61], 0
	v_mov_b64_e32 v[62:63], 0
	v_mov_b64_e32 v[64:65], 0
	v_mov_b64_e32 v[66:67], 0
	v_mov_b64_e32 v[68:69], 0
	v_mov_b64_e32 v[70:71], 0
	v_mov_b64_e32 v[72:73], 0
	v_mov_b64_e32 v[74:75], 0
	v_mov_b64_e32 v[76:77], 0
	v_mov_b64_e32 v[78:79], 0
	v_mov_b64_e32 v[80:81], 0
	v_mov_b64_e32 v[82:83], 0
	v_mov_b64_e32 v[84:85], 0
	v_mov_b64_e32 v[86:87], 0
	v_mov_b64_e32 v[88:89], 0
	v_mov_b64_e32 v[90:91], 0
	v_mov_b64_e32 v[92:93], 0
	v_mov_b64_e32 v[94:95], 0
	v_mov_b64_e32 v[96:97], 0
	v_mov_b64_e32 v[98:99], 0
	v_mov_b64_e32 v[100:101], 0
	v_mov_b64_e32 v[102:103], 0
	v_mov_b64_e32 v[104:105], 0
	v_mov_b64_e32 v[106:107], 0
	v_mov_b64_e32 v[108:109], 0
	v_mov_b64_e32 v[110:111], 0
	v_mov_b64_e32 v[112:113], 0
	v_mov_b64_e32 v[114:115], 0
	v_mov_b64_e32 v[116:117], 0
	v_mov_b64_e32 v[118:119], 0
	v_mov_b64_e32 v[120:121], 0
	v_mov_b64_e32 v[122:123], 0
	v_mov_b64_e32 v[124:125], 0
	v_mov_b64_e32 v[126:127], 0

; template <class Epi, class S_t>
; __device__ __forceinline__ void gemm_phase(LAS unsigned char* lds, int lda, int ldb, const S_t& S, const Epi& E) {
;     ...
; #pragma unroll
;         for (int a = 0; a < 2; ++a)
; #pragma unroll
;             for (int b = 0; b < 2; ++b)
; #pragma unroll
;                 for (int m = 0; m < 4; ++m)
; #pragma unroll
;                     for (int n = 0; n < 2; ++n) acc[a][b][m][n] = (f32x4){0.f, 0.f, 0.f, 0.f};
.LBB0_235:
	s_add_u32 s54, s54, 0x80080
	s_addc_u32 s55, s55, 0
	s_add_u32 s0, s56, 0x100
	s_addc_u32 s1, s57, 0
	s_mov_b32 s7, -2
	v_mov_b64_e32 v[0:1], 0
	v_mov_b64_e32 v[2:3], 0
	v_mov_b64_e32 v[4:5], 0
	v_mov_b64_e32 v[6:7], 0
	v_mov_b64_e32 v[8:9], 0
	v_mov_b64_e32 v[10:11], 0
	v_mov_b64_e32 v[12:13], 0
	v_mov_b64_e32 v[14:15], 0
	v_mov_b64_e32 v[16:17], 0
	v_mov_b64_e32 v[18:19], 0
	v_mov_b64_e32 v[20:21], 0
	v_mov_b64_e32 v[22:23], 0
	v_mov_b64_e32 v[24:25], 0
	v_mov_b64_e32 v[26:27], 0
	v_mov_b64_e32 v[28:29], 0
	v_mov_b64_e32 v[30:31], 0
	v_mov_b64_e32 v[32:33], 0
	v_mov_b64_e32 v[34:35], 0
	v_mov_b64_e32 v[36:37], 0
	v_mov_b64_e32 v[38:39], 0
	v_mov_b64_e32 v[40:41], 0
	v_mov_b64_e32 v[42:43], 0
	v_mov_b64_e32 v[44:45], 0
	v_mov_b64_e32 v[46:47], 0
	v_mov_b64_e32 v[48:49], 0
	v_mov_b64_e32 v[50:51], 0
	v_mov_b64_e32 v[52:53], 0
	v_mov_b64_e32 v[54:55], 0
	v_mov_b64_e32 v[56:57], 0
	v_mov_b64_e32 v[58:59], 0
	v_mov_b64_e32 v[60:61], 0
	v_mov_b64_e32 v[62:63], 0
	v_mov_b64_e32 v[64:65], 0
	v_mov_b64_e32 v[66:67], 0
	v_mov_b64_e32 v[68:69], 0
	v_mov_b64_e32 v[70:71], 0
	v_mov_b64_e32 v[72:73], 0
	v_mov_b64_e32 v[74:75], 0
	v_mov_b64_e32 v[76:77], 0
	v_mov_b64_e32 v[78:79], 0
	v_mov_b64_e32 v[80:81], 0
	v_mov_b64_e32 v[82:83], 0
	v_mov_b64_e32 v[84:85], 0
	v_mov_b64_e32 v[86:87], 0
	v_mov_b64_e32 v[88:89], 0
	v_mov_b64_e32 v[90:91], 0
	v_mov_b64_e32 v[92:93], 0
	v_mov_b64_e32 v[94:95], 0
	v_mov_b64_e32 v[96:97], 0
	v_mov_b64_e32 v[98:99], 0
	v_mov_b64_e32 v[100:101], 0
	v_mov_b64_e32 v[102:103], 0
	v_mov_b64_e32 v[104:105], 0
	v_mov_b64_e32 v[106:107], 0
	v_mov_b64_e32 v[108:109], 0
	v_mov_b64_e32 v[110:111], 0
	v_mov_b64_e32 v[112:113], 0
	v_mov_b64_e32 v[114:115], 0
	v_mov_b64_e32 v[116:117], 0
	v_mov_b64_e32 v[118:119], 0
	v_mov_b64_e32 v[120:121], 0
	v_mov_b64_e32 v[122:123], 0
	v_mov_b64_e32 v[124:125], 0
	v_mov_b64_e32 v[126:127], 0

; template <class Epi, class S_t>
; __device__ __forceinline__ void gemm_phase(LAS unsigned char* lds, int lda, int ldb, const S_t& S, const Epi& E) {
;     ...
; #pragma unroll
;         for (int a = 0; a < 2; ++a)
; #pragma unroll
;             for (int b = 0; b < 2; ++b)
; #pragma unroll
;                 for (int m = 0; m < 4; ++m)
; #pragma unroll
;                     for (int n = 0; n < 2; ++n) acc[a][b][m][n] = (f32x4){0.f, 0.f, 0.f, 0.f};
.LBB0_534:
	s_mov_b32 s0, 0
	s_mov_b64 s[62:63], -1
	s_mov_b64 s[66:67], 0
	v_mov_b64_e32 v[0:1], 0
	v_mov_b64_e32 v[2:3], 0
	v_mov_b64_e32 v[4:5], 0
	v_mov_b64_e32 v[6:7], 0
	v_mov_b64_e32 v[8:9], 0
	v_mov_b64_e32 v[10:11], 0
	v_mov_b64_e32 v[12:13], 0
	v_mov_b64_e32 v[14:15], 0
	v_mov_b64_e32 v[16:17], 0
	v_mov_b64_e32 v[18:19], 0
	v_mov_b64_e32 v[20:21], 0
	v_mov_b64_e32 v[22:23], 0
	v_mov_b64_e32 v[24:25], 0
	v_mov_b64_e32 v[26:27], 0
	v_mov_b64_e32 v[28:29], 0
	v_mov_b64_e32 v[30:31], 0
	v_mov_b64_e32 v[32:33], 0
	v_mov_b64_e32 v[34:35], 0
	v_mov_b64_e32 v[36:37], 0
	v_mov_b64_e32 v[38:39], 0
	v_mov_b64_e32 v[40:41], 0
	v_mov_b64_e32 v[42:43], 0
	v_mov_b64_e32 v[44:45], 0
	v_mov_b64_e32 v[46:47], 0
	v_mov_b64_e32 v[48:49], 0
	v_mov_b64_e32 v[50:51], 0
	v_mov_b64_e32 v[52:53], 0
	v_mov_b64_e32 v[54:55], 0
	v_mov_b64_e32 v[56:57], 0
	v_mov_b64_e32 v[58:59], 0
	v_mov_b64_e32 v[60:61], 0
	v_mov_b64_e32 v[62:63], 0
	v_mov_b64_e32 v[64:65], 0
	v_mov_b64_e32 v[66:67], 0
	v_mov_b64_e32 v[68:69], 0
	v_mov_b64_e32 v[70:71], 0
	v_mov_b64_e32 v[72:73], 0
	v_mov_b64_e32 v[74:75], 0
	v_mov_b64_e32 v[76:77], 0
	v_mov_b64_e32 v[78:79], 0
	v_mov_b64_e32 v[80:81], 0
	v_mov_b64_e32 v[82:83], 0
	v_mov_b64_e32 v[84:85], 0
	v_mov_b64_e32 v[86:87], 0
	v_mov_b64_e32 v[88:89], 0
	v_mov_b64_e32 v[90:91], 0
	v_mov_b64_e32 v[92:93], 0
	v_mov_b64_e32 v[94:95], 0
	v_mov_b64_e32 v[96:97], 0
	v_mov_b64_e32 v[98:99], 0
	v_mov_b64_e32 v[100:101], 0
	v_mov_b64_e32 v[102:103], 0
	v_mov_b64_e32 v[104:105], 0
	v_mov_b64_e32 v[106:107], 0
	v_mov_b64_e32 v[108:109], 0
	v_mov_b64_e32 v[110:111], 0
	v_mov_b64_e32 v[112:113], 0
	v_mov_b64_e32 v[114:115], 0
	v_mov_b64_e32 v[116:117], 0
	v_mov_b64_e32 v[118:119], 0
	v_mov_b64_e32 v[120:121], 0
	v_mov_b64_e32 v[122:123], 0
	v_mov_b64_e32 v[124:125], 0
	v_mov_b64_e32 v[126:127], 0

; #define PG8_STAGE(bufoff, gbase, voff) do { _Pragma("unroll") for (int _i = 0; _i < 2; ++_i) \
;         __builtin_amdgcn_global_load_lds((const unsigned*)((const char*)(gbase) + (voff)[_i]), (LAS unsigned*)(lds + (bufoff) + ldsw + _i * 8192), 16, 0, 0); } while (0)
; #define PG8_LDA(dst, b, h) do { _Pragma("unroll") for (int m = 0; m < 4; ++m) _Pragma("unroll") for (int k = 0; k < 2; ++k) dst[m][k] = *(const LAS bf16x8*)(lds + PG8_SA(b, h) + aoff + m * 2048 + k * 1024); } while (0)
; #define PG8_LDB(dst, b, h) do { _Pragma("unroll") for (int n = 0; n < 2; ++n) _Pragma("unroll") for (int k = 0; k < 2; ++k) dst[n][k] = *(const LAS bf16x8*)(lds + PG8_SB(b, h) + boff + n * 2048 + k * 1024); } while (0)
; #define PG8_MMA(ai, bj, At, Bt) do { __builtin_amdgcn_s_setprio(1); _Pragma("unroll") for (int m = 0; m < 4; ++m) _Pragma("unroll") for (int n = 0; n < 2; ++n) _Pragma("unroll") for (int k = 0; k < 2; ++k) \
;         acc[ai][bj][m][n] = __builtin_amdgcn_mfma_f32_16x16x32_bf16(Bt[n][k], At[m][k], acc[ai][bj][m][n], 0, 0, 0); __builtin_amdgcn_s_setprio(0); } while (0)
; #define PG8_WAIT_L(n) asm volatile("s_waitcnt lgkmcnt(" #n ")" ::: "memory")
; #define PG8_BAR __builtin_amdgcn_s_barrier()
; #define PG8_SCHED __builtin_amdgcn_sched_barrier(0)
; template <class Epi, class S_t>
; __device__ __forceinline__ void gemm_phase(LAS unsigned char* lds, int lda, int ldb, const S_t& S, const Epi& E) {
;     ...
;             PG8_LDB(B0, 0, 0); PG8_SCHED; PG8_LDA(At, 0, 0); PG8_STAGE(PG8_SA(1, 1), a1 + hstepA, voffA);
;             PG8_WAIT_L(8); PG8_BAR; PG8_WAIT_L(0); PG8_MMA(0, 0, At, B0); PG8_BAR; PG8_SCHED;
;             PG8_LDB(B1, 0, 1); PG8_STAGE(PG8_SB(0, 0), b2, voffB);
;             PG8_BAR; PG8_WAIT_L(0); PG8_MMA(0, 1, At, B1); PG8_BAR;
;             PG8_LDA(At, 0, 1); PG8_STAGE(PG8_SA(0, 0), a2, voffA);
;             PG8_BAR; PG8_WAIT_L(0); PG8_MMA(1, 0, At, B0); PG8_BAR; PG8_SCHED;
.LBB0_547:
	s_add_u32 s15, s60, s0
	s_addc_u32 s19, s61, 0
	s_add_u32 s1, s15, 0x100
	s_addc_u32 s33, s19, 0
	s_and_b64 s[70:71], s[68:69], exec
	s_cselect_b32 s75, s57, s33
	s_cselect_b32 s74, s56, s1
	s_add_u32 s0, s62, s0
	s_addc_u32 s1, s63, 0
	s_add_u32 s33, s0, 0x100
	s_addc_u32 s43, s1, 0
	s_and_b64 s[0:1], s[68:69], exec
	s_cselect_b32 s79, s59, s43
	s_cselect_b32 s78, s58, s33
	s_add_u32 s82, s15, 0x80080
	s_addc_u32 s83, s19, 0
	s_add_i32 vcc_hi, s88, s64
	s_add_i32 m0, s53, 0xc000
	s_add_i32 s65, s53, 0xe000
	s_add_i32 s33, vcc_hi, 0x2000
	s_add_u32 s72, s78, 0x10000
	s_addc_u32 s73, s79, 0
	s_add_i32 vcc_lo, s89, s64
	s_add_i32 s43, vcc_lo, 0x2000
	s_add_i32 s90, 0, 0x18000
	ds_read_b128 v[32:35], v226
	ds_read_b128 v[36:39], v226 offset:1024
	ds_read_b128 v[48:51], v226 offset:2048
	ds_read_b128 v[52:55], v226 offset:3072
	s_add_u32 s70, s74, 0x80000
	s_addc_u32 s71, s75, 0
	s_add_i32 s19, s90, s64
	s_add_i32 s91, 0, 0x1c000
	s_add_i32 s15, s19, 0x2000
	s_add_u32 s68, s78, 0x10080
	s_addc_u32 s69, s79, 0
	s_add_i32 s1, s91, s64
	s_add_i32 s0, s1, 0x2000
	ds_read_b128 v[56:59], v227
	ds_read_b128 v[64:67], v227 offset:1024
	ds_read_b128 v[68:71], v227 offset:2048
	ds_read_b128 v[76:79], v227 offset:3072
	ds_read_b128 v[96:99], v227 offset:4096
	ds_read_b128 v[116:119], v227 offset:5120
	ds_read_b128 v[136:139], v227 offset:6144
	ds_read_b128 v[156:159], v227 offset:7168
	global_load_lds_dwordx4 v186, s[82:83]
	s_mov_b32 m0, s65
	s_nop 0
	global_load_lds_dwordx4 v190, s[82:83]
	s_waitcnt lgkmcnt(8)
	s_barrier
	s_waitcnt lgkmcnt(0)
	s_setprio 1
	s_waitcnt lgkmcnt(0)
	v_mfma_f32_16x16x32_bf16 v[172:175], v[32:35], v[56:59], v[172:175]
	v_mfma_f32_16x16x32_bf16 v[168:171], v[48:51], v[56:59], v[168:171]
	v_mfma_f32_16x16x32_bf16 v[152:155], v[32:35], v[68:71], v[152:155]
	v_mfma_f32_16x16x32_bf16 v[148:151], v[48:51], v[68:71], v[148:151]
	v_mfma_f32_16x16x32_bf16 v[132:135], v[32:35], v[96:99], v[132:135]
	v_mfma_f32_16x16x32_bf16 v[128:131], v[48:51], v[96:99], v[128:131]
	v_mfma_f32_16x16x32_bf16 v[112:115], v[32:35], v[136:139], v[112:115]
	v_mfma_f32_16x16x32_bf16 v[108:111], v[48:51], v[136:139], v[108:111]
	v_mfma_f32_16x16x32_bf16 v[172:175], v[36:39], v[64:67], v[172:175]
	v_mfma_f32_16x16x32_bf16 v[168:171], v[52:55], v[64:67], v[168:171]
	v_mfma_f32_16x16x32_bf16 v[152:155], v[36:39], v[76:79], v[152:155]
	v_mfma_f32_16x16x32_bf16 v[148:151], v[52:55], v[76:79], v[148:151]
	v_mfma_f32_16x16x32_bf16 v[132:135], v[36:39], v[116:119], v[132:135]
	v_mfma_f32_16x16x32_bf16 v[128:131], v[52:55], v[116:119], v[128:131]
	v_mfma_f32_16x16x32_bf16 v[112:115], v[36:39], v[156:159], v[112:115]
	v_mfma_f32_16x16x32_bf16 v[108:111], v[52:55], v[156:159], v[108:111]
	s_setprio 0
	s_barrier
	s_mov_b32 m0, vcc_hi
	s_add_u32 s100, s78, s12
	s_addc_u32 s101, s79, s13
	ds_read_b128 v[176:179], v228
	ds_read_b128 v[180:183], v228 offset:1024
	ds_read_b128 v[196:199], v228 offset:2048
	ds_read_b128 v[200:203], v228 offset:3072
	global_load_lds_dwordx4 v188, s[78:79]
	s_mov_b32 m0, s33
	s_nop 0
	global_load_lds_dwordx4 v192, s[78:79]
	s_barrier
	s_waitcnt lgkmcnt(0)
	s_setprio 1
	s_waitcnt lgkmcnt(0)
	v_mfma_f32_16x16x32_bf16 v[160:163], v[176:179], v[56:59], v[160:163]
	v_mfma_f32_16x16x32_bf16 v[56:59], v[196:199], v[56:59], v[164:167]
	v_mfma_f32_16x16x32_bf16 v[160:163], v[180:183], v[64:67], v[160:163]
	v_mfma_f32_16x16x32_bf16 v[56:59], v[200:203], v[64:67], v[56:59]
	v_mfma_f32_16x16x32_bf16 v[64:67], v[176:179], v[68:71], v[140:143]
	v_mfma_f32_16x16x32_bf16 v[68:71], v[196:199], v[68:71], v[144:147]
	v_mfma_f32_16x16x32_bf16 v[100:103], v[176:179], v[136:139], v[100:103]
	v_mfma_f32_16x16x32_bf16 v[104:107], v[196:199], v[136:139], v[104:107]
	v_mfma_f32_16x16x32_bf16 v[64:67], v[180:183], v[76:79], v[64:67]
	v_mfma_f32_16x16x32_bf16 v[68:71], v[200:203], v[76:79], v[68:71]
	v_mfma_f32_16x16x32_bf16 v[76:79], v[176:179], v[96:99], v[120:123]
	v_mfma_f32_16x16x32_bf16 v[96:99], v[196:199], v[96:99], v[124:127]
	v_mfma_f32_16x16x32_bf16 v[100:103], v[180:183], v[156:159], v[100:103]
	v_mfma_f32_16x16x32_bf16 v[104:107], v[200:203], v[156:159], v[104:107]
	v_mfma_f32_16x16x32_bf16 v[76:79], v[180:183], v[116:119], v[76:79]
	v_mfma_f32_16x16x32_bf16 v[96:99], v[200:203], v[116:119], v[96:99]
	s_setprio 0
	s_mov_b32 m0, s53
	s_add_u32 s98, s74, s12
	s_addc_u32 s99, s75, s13
	s_barrier
	ds_read_b128 v[116:119], v227 offset:16384
	ds_read_b128 v[120:123], v227 offset:17408
	ds_read_b128 v[124:127], v227 offset:18432
	ds_read_b128 v[136:139], v227 offset:19456
	ds_read_b128 v[140:143], v227 offset:20480
	ds_read_b128 v[144:147], v227 offset:21504
	ds_read_b128 v[156:159], v227 offset:22528
	ds_read_b128 v[164:167], v227 offset:23552
	global_load_lds_dwordx4 v186, s[74:75]
	s_mov_b32 m0, s95
	s_nop 0
	global_load_lds_dwordx4 v190, s[74:75]
	s_barrier
	s_waitcnt lgkmcnt(0)
	s_setprio 1
	s_waitcnt lgkmcnt(0)
	v_mfma_f32_16x16x32_bf16 v[92:95], v[32:35], v[116:119], v[92:95]
	v_mfma_f32_16x16x32_bf16 v[88:91], v[48:51], v[116:119], v[88:91]
	v_mfma_f32_16x16x32_bf16 v[72:75], v[32:35], v[124:127], v[72:75]
	v_mfma_f32_16x16x32_bf16 v[60:63], v[48:51], v[124:127], v[60:63]
	v_mfma_f32_16x16x32_bf16 v[28:31], v[32:35], v[140:143], v[28:31]
	v_mfma_f32_16x16x32_bf16 v[24:27], v[48:51], v[140:143], v[24:27]
	v_mfma_f32_16x16x32_bf16 v[12:15], v[32:35], v[156:159], v[12:15]
	v_mfma_f32_16x16x32_bf16 v[8:11], v[48:51], v[156:159], v[8:11]
	v_mfma_f32_16x16x32_bf16 v[92:95], v[36:39], v[120:123], v[92:95]
	v_mfma_f32_16x16x32_bf16 v[88:91], v[52:55], v[120:123], v[88:91]
	v_mfma_f32_16x16x32_bf16 v[72:75], v[36:39], v[136:139], v[72:75]
	v_mfma_f32_16x16x32_bf16 v[60:63], v[52:55], v[136:139], v[60:63]
	v_mfma_f32_16x16x32_bf16 v[28:31], v[36:39], v[144:147], v[28:31]
	v_mfma_f32_16x16x32_bf16 v[24:27], v[52:55], v[144:147], v[24:27]
	v_mfma_f32_16x16x32_bf16 v[12:15], v[36:39], v[164:167], v[12:15]
	v_mfma_f32_16x16x32_bf16 v[8:11], v[52:55], v[164:167], v[8:11]
	s_setprio 0
	s_barrier
; #define PG8_STAGE(bufoff, gbase, voff) do { _Pragma("unroll") for (int _i = 0; _i < 2; ++_i) \
;         __builtin_amdgcn_global_load_lds((const unsigned*)((const char*)(gbase) + (voff)[_i]), (LAS unsigned*)(lds + (bufoff) + ldsw + _i * 8192), 16, 0, 0); } while (0)
; #define PG8_LDA(dst, b, h) do { _Pragma("unroll") for (int m = 0; m < 4; ++m) _Pragma("unroll") for (int k = 0; k < 2; ++k) dst[m][k] = *(const LAS bf16x8*)(lds + PG8_SA(b, h) + aoff + m * 2048 + k * 1024); } while (0)
; #define PG8_LDB(dst, b, h) do { _Pragma("unroll") for (int n = 0; n < 2; ++n) _Pragma("unroll") for (int k = 0; k < 2; ++k) dst[n][k] = *(const LAS bf16x8*)(lds + PG8_SB(b, h) + boff + n * 2048 + k * 1024); } while (0)
; #define PG8_MMA(ai, bj, At, Bt) do { __builtin_amdgcn_s_setprio(1); _Pragma("unroll") for (int m = 0; m < 4; ++m) _Pragma("unroll") for (int n = 0; n < 2; ++n) _Pragma("unroll") for (int k = 0; k < 2; ++k) \
;         acc[ai][bj][m][n] = __builtin_amdgcn_mfma_f32_16x16x32_bf16(Bt[n][k], At[m][k], acc[ai][bj][m][n], 0, 0, 0); __builtin_amdgcn_s_setprio(0); } while (0)
; #define PG8_WAIT_V(n) asm volatile("s_waitcnt vmcnt(" #n ")" ::: "memory")
; #define PG8_WAIT_L(n) asm volatile("s_waitcnt lgkmcnt(" #n ")" ::: "memory")
; #define PG8_BAR __builtin_amdgcn_s_barrier()
; #define PG8_SCHED __builtin_amdgcn_sched_barrier(0)
; template <class Epi, class S_t>
; __device__ __forceinline__ void gemm_phase(LAS unsigned char* lds, int lda, int ldb, const S_t& S, const Epi& E) {
;     ...
;             PG8_STAGE(PG8_SB(0, 1), b2 + hstepB, voffB);
;             PG8_WAIT_V(6); PG8_BAR; PG8_MMA(1, 1, At, B1); PG8_BAR;
;             PG8_LDB(B0, 1, 0); PG8_SCHED; PG8_LDA(At, 1, 0); PG8_STAGE(PG8_SA(0, 1), a2 + hstepA, voffA);
;             PG8_WAIT_L(8); PG8_BAR; PG8_WAIT_L(0); PG8_MMA(0, 0, At, B0); PG8_BAR; PG8_SCHED;
;             PG8_LDB(B1, 1, 1); PG8_STAGE(PG8_SB(1, 0), b3, voffB);
;             PG8_BAR; PG8_WAIT_L(0); PG8_MMA(0, 1, At, B1); PG8_BAR;
	s_mov_b32 m0, vcc_lo
	global_load_lds_dwordx4 v188, s[72:73]
	s_mov_b32 m0, s43
	s_nop 0
	global_load_lds_dwordx4 v192, s[72:73]
	s_waitcnt vmcnt(6)
	s_barrier
	s_setprio 1
	v_mfma_f32_16x16x32_bf16 v[40:43], v[176:179], v[124:127], v[40:43]
	v_mfma_f32_16x16x32_bf16 v[44:47], v[196:199], v[124:127], v[44:47]
	v_mfma_f32_16x16x32_bf16 v[16:19], v[176:179], v[140:143], v[16:19]
	v_mfma_f32_16x16x32_bf16 v[20:23], v[196:199], v[140:143], v[20:23]
	v_mfma_f32_16x16x32_bf16 v[0:3], v[176:179], v[156:159], v[0:3]
	v_mfma_f32_16x16x32_bf16 v[4:7], v[196:199], v[156:159], v[4:7]
	v_mfma_f32_16x16x32_bf16 v[32:35], v[176:179], v[116:119], v[80:83]
	v_mfma_f32_16x16x32_bf16 v[36:39], v[196:199], v[116:119], v[84:87]
	v_mfma_f32_16x16x32_bf16 v[40:43], v[180:183], v[136:139], v[40:43]
	v_mfma_f32_16x16x32_bf16 v[44:47], v[200:203], v[136:139], v[44:47]
	v_mfma_f32_16x16x32_bf16 v[16:19], v[180:183], v[144:147], v[16:19]
	v_mfma_f32_16x16x32_bf16 v[20:23], v[200:203], v[144:147], v[20:23]
	v_mfma_f32_16x16x32_bf16 v[0:3], v[180:183], v[164:167], v[0:3]
	v_mfma_f32_16x16x32_bf16 v[4:7], v[200:203], v[164:167], v[4:7]
	v_mfma_f32_16x16x32_bf16 v[32:35], v[180:183], v[120:123], v[32:35]
	v_mfma_f32_16x16x32_bf16 v[36:39], v[200:203], v[120:123], v[36:39]
	s_setprio 0
	v_add_u32_e32 v84, s90, v219
	s_barrier
	ds_read_b128 v[48:51], v84
	ds_read_b128 v[52:55], v84 offset:1024
	ds_read_b128 v[80:83], v84 offset:2048
	ds_read_b128 v[84:87], v84 offset:3072
	s_mov_b32 m0, s96
	ds_read_b128 v[116:119], v227 offset:32768
	ds_read_b128 v[120:123], v227 offset:33792
	ds_read_b128 v[124:127], v227 offset:34816
	ds_read_b128 v[136:139], v227 offset:35840
	ds_read_b128 v[156:159], v227 offset:36864
	ds_read_b128 v[176:179], v227 offset:37888
	ds_read_b128 v[180:183], v227 offset:38912
	ds_read_b128 v[196:199], v227 offset:39936
	global_load_lds_dwordx4 v186, s[70:71]
	s_mov_b32 m0, s97
	s_nop 0
	global_load_lds_dwordx4 v190, s[70:71]
	s_waitcnt lgkmcnt(8)
	s_barrier
	s_waitcnt lgkmcnt(0)
	s_setprio 1
	s_waitcnt lgkmcnt(0)
	v_mfma_f32_16x16x32_bf16 v[140:143], v[48:51], v[116:119], v[172:175]
	v_mfma_f32_16x16x32_bf16 v[172:175], v[52:55], v[120:123], v[140:143]
	v_mfma_f32_16x16x32_bf16 v[140:143], v[80:83], v[116:119], v[168:171]
	v_mfma_f32_16x16x32_bf16 v[168:171], v[84:87], v[120:123], v[140:143]
	v_mfma_f32_16x16x32_bf16 v[140:143], v[48:51], v[124:127], v[152:155]
	v_mfma_f32_16x16x32_bf16 v[152:155], v[52:55], v[136:139], v[140:143]
	v_mfma_f32_16x16x32_bf16 v[140:143], v[80:83], v[124:127], v[148:151]
	v_mfma_f32_16x16x32_bf16 v[132:135], v[48:51], v[156:159], v[132:135]
	v_mfma_f32_16x16x32_bf16 v[128:131], v[80:83], v[156:159], v[128:131]
	v_mfma_f32_16x16x32_bf16 v[112:115], v[48:51], v[180:183], v[112:115]
	v_mfma_f32_16x16x32_bf16 v[108:111], v[80:83], v[180:183], v[108:111]
	v_mfma_f32_16x16x32_bf16 v[148:151], v[84:87], v[136:139], v[140:143]
	v_mfma_f32_16x16x32_bf16 v[132:135], v[52:55], v[176:179], v[132:135]
	v_mfma_f32_16x16x32_bf16 v[128:131], v[84:87], v[176:179], v[128:131]
	v_mfma_f32_16x16x32_bf16 v[112:115], v[52:55], v[196:199], v[112:115]
	v_mfma_f32_16x16x32_bf16 v[108:111], v[84:87], v[196:199], v[108:111]
	s_setprio 0
	s_barrier
	v_add_u32_e32 v140, s91, v219
	s_mov_b32 m0, s19
	ds_read_b128 v[200:203], v140
	ds_read_b128 v[204:207], v140 offset:1024
	ds_read_b128 v[222:225], v140 offset:2048
	ds_read_b128 v[234:237], v140 offset:3072
	global_load_lds_dwordx4 v188, s[100:101]
	s_mov_b32 m0, s15
	s_nop 0
	global_load_lds_dwordx4 v192, s[100:101]
	s_barrier
	s_waitcnt lgkmcnt(0)
	s_setprio 1
	s_waitcnt lgkmcnt(0)
	v_mfma_f32_16x16x32_bf16 v[56:59], v[222:225], v[116:119], v[56:59]
	v_mfma_f32_16x16x32_bf16 v[140:143], v[200:203], v[116:119], v[160:163]
	v_mfma_f32_16x16x32_bf16 v[164:167], v[234:237], v[120:123], v[56:59]
	v_mfma_f32_16x16x32_bf16 v[56:59], v[200:203], v[124:127], v[64:67]
	v_mfma_f32_16x16x32_bf16 v[160:163], v[204:207], v[120:123], v[140:143]
	v_mfma_f32_16x16x32_bf16 v[140:143], v[204:207], v[136:139], v[56:59]
	v_mfma_f32_16x16x32_bf16 v[56:59], v[222:225], v[124:127], v[68:71]
	v_mfma_f32_16x16x32_bf16 v[144:147], v[234:237], v[136:139], v[56:59]
	v_mfma_f32_16x16x32_bf16 v[56:59], v[200:203], v[156:159], v[76:79]
	v_mfma_f32_16x16x32_bf16 v[120:123], v[204:207], v[176:179], v[56:59]
	v_mfma_f32_16x16x32_bf16 v[56:59], v[222:225], v[156:159], v[96:99]
	v_mfma_f32_16x16x32_bf16 v[124:127], v[234:237], v[176:179], v[56:59]
	v_mfma_f32_16x16x32_bf16 v[56:59], v[200:203], v[180:183], v[100:103]
	v_mfma_f32_16x16x32_bf16 v[100:103], v[204:207], v[196:199], v[56:59]
	v_mfma_f32_16x16x32_bf16 v[56:59], v[222:225], v[180:183], v[104:107]
	v_mfma_f32_16x16x32_bf16 v[104:107], v[234:237], v[196:199], v[56:59]
	s_setprio 0
	s_mov_b32 m0, s16
	s_barrier
	s_nop 2
	ds_read_b128 v[56:59], v227 offset:49152
	ds_read_b128 v[64:67], v227 offset:50176
	ds_read_b128 v[68:71], v227 offset:51200
	ds_read_b128 v[76:79], v227 offset:52224
	ds_read_b128 v[96:99], v227 offset:53248
	ds_read_b128 v[116:119], v227 offset:54272
	ds_read_b128 v[136:139], v227 offset:55296
	ds_read_b128 v[156:159], v227 offset:56320
	global_load_lds_dwordx4 v186, s[98:99]
	s_mov_b32 m0, s17
	s_nop 0
	global_load_lds_dwordx4 v190, s[98:99]
	s_barrier
; #define PG8_STAGE(bufoff, gbase, voff) do { _Pragma("unroll") for (int _i = 0; _i < 2; ++_i) \
;         __builtin_amdgcn_global_load_lds((const unsigned*)((const char*)(gbase) + (voff)[_i]), (LAS unsigned*)(lds + (bufoff) + ldsw + _i * 8192), 16, 0, 0); } while (0)
; #define PG8_LDA(dst, b, h) do { _Pragma("unroll") for (int m = 0; m < 4; ++m) _Pragma("unroll") for (int k = 0; k < 2; ++k) dst[m][k] = *(const LAS bf16x8*)(lds + PG8_SA(b, h) + aoff + m * 2048 + k * 1024); } while (0)
; #define PG8_MMA(ai, bj, At, Bt) do { __builtin_amdgcn_s_setprio(1); _Pragma("unroll") for (int m = 0; m < 4; ++m) _Pragma("unroll") for (int n = 0; n < 2; ++n) _Pragma("unroll") for (int k = 0; k < 2; ++k) \
;         acc[ai][bj][m][n] = __builtin_amdgcn_mfma_f32_16x16x32_bf16(Bt[n][k], At[m][k], acc[ai][bj][m][n], 0, 0, 0); __builtin_amdgcn_s_setprio(0); } while (0)
; #define PG8_WAIT_V(n) asm volatile("s_waitcnt vmcnt(" #n ")" ::: "memory")
; #define PG8_WAIT_L(n) asm volatile("s_waitcnt lgkmcnt(" #n ")" ::: "memory")
; #define PG8_BAR __builtin_amdgcn_s_barrier()
; #define PG8_SCHED __builtin_amdgcn_sched_barrier(0)
; template <class Epi, class S_t>
; __device__ __forceinline__ void gemm_phase(LAS unsigned char* lds, int lda, int ldb, const S_t& S, const Epi& E) {
;     ...
;             PG8_LDA(At, 1, 1); PG8_STAGE(PG8_SA(1, 0), a3, voffA);
;             PG8_BAR; PG8_WAIT_L(0); PG8_MMA(1, 0, At, B0); PG8_BAR; PG8_SCHED;
;             PG8_STAGE(PG8_SB(1, 1), b3 + hstepB, voffB);
;             PG8_WAIT_V(6); PG8_BAR; PG8_MMA(1, 1, At, B1); PG8_BAR;
;     __device__ __forceinline__ void operator()(const f32x4 (&acc)[2][2][4][2], const Unit& u, int wr, int wc, int fr, int fq) const {
;         const int row0 = u.pm * BM + wr * 64 + fr, ch0 = u.pn * HALF + wc * 32 + 8 * fq;
;         float br[8], bi[8], sp[8];
; #pragma unroll
;         for (int q = 0; q < 2; ++q) { const f32x4 a = *(const f32x4*)(brg + ch0 + 4 * q), b = *(const f32x4*)(big + ch0 + 4 * q), c = *(const f32x4*)(spl + ch0 + 4 * q);
; #pragma unroll
;             for (int j = 0; j < 4; ++j) { br[4 * q + j] = a[j]; bi[4 * q + j] = b[j]; sp[4 * q + j] = c[j]; } }
;         u32x4 xraw[2][4];
; #pragma unroll
;         for (int ai = 0; ai < 2; ++ai)
; #pragma unroll
;             for (int m = 0; m < 4; ++m) xraw[ai][m] = *(const u32x4*)(XC + (size_t)(row0 + ai * HALF + m * 16) * LW + ch0);
	s_waitcnt lgkmcnt(0)
	s_setprio 1
	s_waitcnt lgkmcnt(0)
	v_mfma_f32_16x16x32_bf16 v[92:95], v[48:51], v[56:59], v[92:95]
	v_mfma_f32_16x16x32_bf16 v[88:91], v[80:83], v[56:59], v[88:91]
	v_mfma_f32_16x16x32_bf16 v[72:75], v[48:51], v[68:71], v[72:75]
	v_mfma_f32_16x16x32_bf16 v[60:63], v[80:83], v[68:71], v[60:63]
	v_mfma_f32_16x16x32_bf16 v[28:31], v[48:51], v[96:99], v[28:31]
	v_mfma_f32_16x16x32_bf16 v[24:27], v[80:83], v[96:99], v[24:27]
	v_mfma_f32_16x16x32_bf16 v[12:15], v[48:51], v[136:139], v[12:15]
	v_mfma_f32_16x16x32_bf16 v[8:11], v[80:83], v[136:139], v[8:11]
	v_mfma_f32_16x16x32_bf16 v[92:95], v[52:55], v[64:67], v[92:95]
	v_mfma_f32_16x16x32_bf16 v[88:91], v[84:87], v[64:67], v[88:91]
	v_mfma_f32_16x16x32_bf16 v[72:75], v[52:55], v[76:79], v[72:75]
	v_mfma_f32_16x16x32_bf16 v[60:63], v[84:87], v[76:79], v[60:63]
	v_mfma_f32_16x16x32_bf16 v[28:31], v[52:55], v[116:119], v[28:31]
	v_mfma_f32_16x16x32_bf16 v[24:27], v[84:87], v[116:119], v[24:27]
	v_mfma_f32_16x16x32_bf16 v[12:15], v[52:55], v[156:159], v[12:15]
	v_mfma_f32_16x16x32_bf16 v[8:11], v[84:87], v[156:159], v[8:11]
	s_setprio 0
	s_barrier
	s_mov_b32 m0, s1
	global_load_lds_dwordx4 v188, s[68:69]
	s_mov_b32 m0, s0
	s_nop 0
	global_load_lds_dwordx4 v192, s[68:69]
	s_waitcnt vmcnt(6)
	s_barrier
	s_setprio 1
	v_mfma_f32_16x16x32_bf16 v[32:35], v[200:203], v[56:59], v[32:35]
	v_mfma_f32_16x16x32_bf16 v[80:83], v[204:207], v[64:67], v[32:35]
	v_mfma_f32_16x16x32_bf16 v[32:35], v[222:225], v[56:59], v[36:39]
	v_mfma_f32_16x16x32_bf16 v[84:87], v[234:237], v[64:67], v[32:35]
	v_mfma_f32_16x16x32_bf16 v[32:35], v[200:203], v[68:71], v[40:43]
	v_mfma_f32_16x16x32_bf16 v[40:43], v[204:207], v[76:79], v[32:35]
	v_mfma_f32_16x16x32_bf16 v[32:35], v[222:225], v[68:71], v[44:47]
	v_mfma_f32_16x16x32_bf16 v[16:19], v[200:203], v[96:99], v[16:19]
	v_mfma_f32_16x16x32_bf16 v[20:23], v[222:225], v[96:99], v[20:23]
	v_mfma_f32_16x16x32_bf16 v[0:3], v[200:203], v[136:139], v[0:3]
	v_mfma_f32_16x16x32_bf16 v[4:7], v[222:225], v[136:139], v[4:7]
	v_mfma_f32_16x16x32_bf16 v[44:47], v[234:237], v[76:79], v[32:35]
	v_mfma_f32_16x16x32_bf16 v[16:19], v[204:207], v[116:119], v[16:19]
	v_mfma_f32_16x16x32_bf16 v[20:23], v[234:237], v[116:119], v[20:23]
	v_mfma_f32_16x16x32_bf16 v[0:3], v[204:207], v[156:159], v[0:3]
	v_mfma_f32_16x16x32_bf16 v[4:7], v[234:237], v[156:159], v[4:7]
	s_setprio 0
	s_movk_i32 s0, 0x100
	s_andn2_b64 vcc, exec, s[66:67]
	s_mov_b64 s[68:69], -1
	s_mov_b64 s[66:67], 0
	s_barrier
	s_cbranch_vccz .LBB0_547
	v_lshl_or_b32 v196, s42, 7, v221
	v_readlane_b32 s68, v254, 49
	v_ashrrev_i32_e32 v197, 31, v196
	v_readlane_b32 s76, v254, 57
	v_readlane_b32 s77, v254, 58
	v_lshlrev_b64 v[32:33], 2, v[196:197]
	v_readlane_b32 s80, v254, 61
	v_readlane_b32 s81, v254, 62
	s_mov_b64 s[24:25], s[76:77]
	s_mov_b64 s[28:29], s[80:81]
	v_lshl_add_u64 v[34:35], s[24:25], 0, v[32:33]
	v_lshl_add_u64 v[48:49], s[28:29], 0, v[32:33]
	v_lshl_add_u64 v[50:51], s[10:11], 0, v[32:33]
	global_load_dwordx4 v[56:59], v[34:35], off offset:16
	global_load_dwordx4 v[68:71], v[34:35], off
	global_load_dwordx4 v[36:39], v[48:49], off offset:16
	s_nop 0
	global_load_dwordx4 v[32:35], v[48:49], off
	global_load_dwordx4 v[52:55], v[50:51], off offset:16
	global_load_dwordx4 v[64:67], v[50:51], off
	v_lshl_add_u32 v224, s5, 8, v215
	v_or_b32_e32 v222, 16, v224
	v_ashrrev_i32_e32 v225, 31, v224
	v_ashrrev_i32_e32 v223, 31, v222
	v_lshl_add_u64 v[48:49], v[196:197], 1, s[8:9]
	v_lshlrev_b64 v[50:51], 12, v[224:225]
	v_lshlrev_b64 v[76:77], 12, v[222:223]
	v_or_b32_e32 v208, 32, v224
	v_or_b32_e32 v206, 48, v224
	v_lshl_add_u64 v[50:51], v[48:49], 0, v[50:51]
	v_lshl_add_u64 v[76:77], v[48:49], 0, v[76:77]
	v_ashrrev_i32_e32 v209, 31, v208
	v_ashrrev_i32_e32 v207, 31, v206
	global_load_dwordx4 v[180:183], v[50:51], off
	global_load_dwordx4 v[176:179], v[76:77], off
	v_lshlrev_b64 v[50:51], 12, v[208:209]
	v_lshlrev_b64 v[76:77], 12, v[206:207]
	v_add_u32_e32 v204, 0x80, v224
	v_add_u32_e32 v202, 0x90, v224
	v_lshl_add_u64 v[50:51], v[48:49], 0, v[50:51]
	v_lshl_add_u64 v[76:77], v[48:49], 0, v[76:77]
	v_ashrrev_i32_e32 v205, 31, v204
	v_ashrrev_i32_e32 v203, 31, v202
	global_load_dwordx4 v[156:159], v[50:51], off
	global_load_dwordx4 v[136:139], v[76:77], off
	v_lshlrev_b64 v[50:51], 12, v[204:205]
	v_lshlrev_b64 v[76:77], 12, v[202:203]
	v_add_u32_e32 v200, 0xa0, v224
	v_add_u32_e32 v198, 0xb0, v224
	v_lshl_add_u64 v[50:51], v[48:49], 0, v[50:51]
	v_lshl_add_u64 v[76:77], v[48:49], 0, v[76:77]
	v_ashrrev_i32_e32 v201, 31, v200
	v_ashrrev_i32_e32 v199, 31, v198
	global_load_dwordx4 v[116:119], v[50:51], off
	global_load_dwordx4 v[96:99], v[76:77], off
	v_lshlrev_b64 v[50:51], 12, v[200:201]
	v_lshlrev_b64 v[76:77], 12, v[198:199]
	v_lshl_add_u64 v[50:51], v[48:49], 0, v[50:51]
	v_lshl_add_u64 v[48:49], v[48:49], 0, v[76:77]
	global_load_dwordx4 v[76:79], v[50:51], off
	s_nop 0
	global_load_dwordx4 v[48:51], v[48:49], off
	v_readlane_b32 s69, v254, 50
	v_readlane_b32 s70, v254, 51
	v_readlane_b32 s71, v254, 52
	v_readlane_b32 s72, v254, 53
	v_readlane_b32 s73, v254, 54
	v_readlane_b32 s74, v254, 55
	v_readlane_b32 s75, v254, 56
	v_readlane_b32 s78, v254, 59
	v_readlane_b32 s79, v254, 60
	v_readlane_b32 s82, v254, 63
	v_readlane_b32 s83, v255, 0
	s_waitcnt vmcnt(8)
; __device__ __forceinline__ float sigmoidf_(float x) { return __builtin_amdgcn_rcpf(1.0f + __expf(-x)); }
;     __device__ __forceinline__ void operator()(const f32x4 (&acc)[2][2][4][2], const Unit& u, int wr, int wc, int fr, int fq) const {
;     ...
;         for (int ai = 0; ai < 2; ++ai)
; #pragma unroll
;             for (int m = 0; m < 4; ++m) { const size_t off = (size_t)(row0 + ai * HALF + m * 16) * LW + ch0;
;                 float xc[8]; unpack8(xraw[ai][m], xc);
;                 float la[8], uu[8];
; #pragma unroll
;                 for (int n = 0; n < 2; ++n)
; #pragma unroll
;                     for (int j = 0; j < 4; ++j) { const int e = 4 * n + j;
;                         const float r = sigmoidf_(acc[ai][0][m][n][j] + br[e]), ig = sigmoidf_(acc[ai][1][m][n][j] + bi[e]);
;                         const float l = -8.0f * r * sp[e]; la[e] = l;
;                         const float x2 = 2.0f * l;
;                         const float om = x2 > -0.03125f ? -x2 * (1.0f + x2 * (0.5f + x2 * (0.16666667f + x2 * 0.041666668f))) : 1.0f - __expf(x2);
;                         uu[e] = __builtin_amdgcn_sqrtf(om) * (ig * xc[e]); }
	s_mov_b32 s68, 0xbfb8aa3b
	s_mov_b32 s69, 0xbfb8aa3b
	s_mov_b32 s70, 0x3fb8aa3b
	s_mov_b32 s71, 0x3fb8aa3b
	s_mov_b32 s72, 1.0
	s_mov_b32 s73, 1.0
	s_mov_b32 s74, 0x3d2aaaab
	s_mov_b32 s75, 0x3d2aaaab
	s_mov_b32 s76, 0.5
	s_mov_b32 s77, 0.5
	v_mov_b32_e32 v222, v229
	v_mov_b32_e32 v223, v229
	v_mul_f32_e32 v64, 0xc1000000, v64
	v_mul_f32_e32 v65, 0xc1000000, v65
	v_mul_f32_e32 v66, 0xc1000000, v66
	v_mul_f32_e32 v67, 0xc1000000, v67
	v_mul_f32_e32 v52, 0xc1000000, v52
	v_mul_f32_e32 v53, 0xc1000000, v53
	v_mul_f32_e32 v54, 0xc1000000, v54
	v_mul_f32_e32 v55, 0xc1000000, v55
	v_lshlrev_b32_e32 v225, 13, v224
	v_lshl_add_u32 v225, v196, 2, v225
	v_pk_add_f32 v[172:173], v[172:173], v[68:69]
	v_pk_add_f32 v[160:161], v[160:161], v[32:33]
	v_pk_add_f32 v[174:175], v[174:175], v[70:71]
	v_pk_add_f32 v[162:163], v[162:163], v[34:35]
	v_pk_add_f32 v[168:169], v[168:169], v[56:57]
	v_pk_add_f32 v[164:165], v[164:165], v[36:37]
	v_pk_add_f32 v[170:171], v[170:171], v[58:59]
	v_pk_add_f32 v[166:167], v[166:167], v[38:39]
	v_pk_mul_f32 v[172:173], v[172:173], s[68:69]
	v_pk_mul_f32 v[160:161], v[160:161], s[68:69]
	v_pk_mul_f32 v[174:175], v[174:175], s[68:69]
	v_pk_mul_f32 v[162:163], v[162:163], s[68:69]
	v_pk_mul_f32 v[168:169], v[168:169], s[68:69]
	v_pk_mul_f32 v[164:165], v[164:165], s[68:69]
	v_pk_mul_f32 v[170:171], v[170:171], s[68:69]
	v_pk_mul_f32 v[166:167], v[166:167], s[68:69]
	v_exp_f32_e32 v172, v172
	v_exp_f32_e32 v173, v173
	v_exp_f32_e32 v174, v174
	v_exp_f32_e32 v175, v175
	v_exp_f32_e32 v168, v168
	v_exp_f32_e32 v169, v169
	v_exp_f32_e32 v170, v170
	v_exp_f32_e32 v171, v171
	v_exp_f32_e32 v160, v160
	v_exp_f32_e32 v161, v161
	v_exp_f32_e32 v162, v162
	v_exp_f32_e32 v163, v163
	v_exp_f32_e32 v164, v164
	v_exp_f32_e32 v165, v165
	v_exp_f32_e32 v166, v166
	v_exp_f32_e32 v167, v167
	v_pk_add_f32 v[172:173], v[172:173], s[72:73]
	v_pk_add_f32 v[160:161], v[160:161], s[72:73]
	v_pk_add_f32 v[174:175], v[174:175], s[72:73]
	v_pk_add_f32 v[162:163], v[162:163], s[72:73]
	v_pk_add_f32 v[168:169], v[168:169], s[72:73]
	v_pk_add_f32 v[164:165], v[164:165], s[72:73]
	v_pk_add_f32 v[170:171], v[170:171], s[72:73]
	v_pk_add_f32 v[166:167], v[166:167], s[72:73]
	v_rcp_f32_e32 v172, v172
	v_rcp_f32_e32 v173, v173
	v_rcp_f32_e32 v174, v174
	v_rcp_f32_e32 v175, v175
	v_rcp_f32_e32 v168, v168
	v_rcp_f32_e32 v169, v169
	v_rcp_f32_e32 v170, v170
	v_rcp_f32_e32 v171, v171
	v_rcp_f32_e32 v160, v160
	v_rcp_f32_e32 v161, v161
	v_rcp_f32_e32 v162, v162
	v_rcp_f32_e32 v163, v163
	v_rcp_f32_e32 v164, v164
	v_rcp_f32_e32 v165, v165
	v_rcp_f32_e32 v166, v166
	v_rcp_f32_e32 v167, v167
	s_waitcnt vmcnt(7)
	v_lshlrev_b32_e32 v230, 16, v180
	v_and_b32_e32 v231, 0xffff0000, v180
	v_lshlrev_b32_e32 v234, 16, v181
	v_and_b32_e32 v235, 0xffff0000, v181
	v_lshlrev_b32_e32 v236, 16, v182
	v_and_b32_e32 v237, 0xffff0000, v182
	v_lshlrev_b32_e32 v238, 16, v183
	v_and_b32_e32 v239, 0xffff0000, v183
	v_pk_mul_f32 v[172:173], v[64:65], v[172:173]
	v_pk_mul_f32 v[174:175], v[66:67], v[174:175]
	v_pk_mul_f32 v[168:169], v[52:53], v[168:169]
	v_pk_mul_f32 v[170:171], v[54:55], v[170:171]
	v_pk_mul_f32 v[160:161], v[160:161], v[230:231]
	v_pk_mul_f32 v[162:163], v[162:163], v[234:235]
	v_pk_mul_f32 v[164:165], v[164:165], v[236:237]
	v_pk_mul_f32 v[166:167], v[166:167], v[238:239]
	v_pk_add_f32 v[198:199], v[172:173], v[172:173]
	v_pk_add_f32 v[200:201], v[174:175], v[174:175]
	v_pk_mul_f32 v[206:207], v[198:199], s[70:71]
	v_pk_mul_f32 v[208:209], v[200:201], s[70:71]
	v_pk_fma_f32 v[202:203], v[198:199], s[74:75], v[222:223]
	v_pk_fma_f32 v[204:205], v[200:201], s[74:75], v[222:223]
	v_exp_f32_e32 v206, v206
	v_exp_f32_e32 v207, v207
	v_exp_f32_e32 v208, v208
	v_exp_f32_e32 v209, v209
	v_pk_fma_f32 v[202:203], v[198:199], v[202:203], s[76:77]
	v_pk_fma_f32 v[204:205], v[200:201], v[204:205], s[76:77]
	v_pk_fma_f32 v[202:203], v[198:199], v[202:203], s[72:73]
	v_pk_fma_f32 v[204:205], v[200:201], v[204:205], s[72:73]
	v_pk_mul_f32 v[202:203], v[202:203], v[198:199] neg_lo:[0,1] neg_hi:[0,1]
	v_pk_mul_f32 v[204:205], v[204:205], v[200:201] neg_lo:[0,1] neg_hi:[0,1]
	v_pk_add_f32 v[206:207], s[72:73], v[206:207] neg_lo:[0,1] neg_hi:[0,1]
	v_pk_add_f32 v[208:209], s[72:73], v[208:209] neg_lo:[0,1] neg_hi:[0,1]
	v_cmp_lt_f32_e64 s[78:79], s4, v198
	v_cmp_lt_f32_e64 s[80:81], s4, v199
	v_cmp_lt_f32_e64 s[82:83], s4, v200
	v_cmp_lt_f32_e64 s[24:25], s4, v201
	v_cndmask_b32_e64 v202, v206, v202, s[78:79]
	v_cndmask_b32_e64 v203, v207, v203, s[80:81]
	v_cndmask_b32_e64 v204, v208, v204, s[82:83]
	v_cndmask_b32_e64 v205, v209, v205, s[24:25]
	v_sqrt_f32_e32 v202, v202
	v_sqrt_f32_e32 v203, v203
	v_sqrt_f32_e32 v204, v204
	v_sqrt_f32_e32 v205, v205
	v_pk_mul_f32 v[160:161], v[160:161], v[202:203]
	v_pk_mul_f32 v[162:163], v[162:163], v[204:205]
	v_pk_add_f32 v[198:199], v[168:169], v[168:169]
	v_pk_add_f32 v[200:201], v[170:171], v[170:171]
	v_pk_mul_f32 v[206:207], v[198:199], s[70:71]
	v_pk_mul_f32 v[208:209], v[200:201], s[70:71]
	v_pk_fma_f32 v[202:203], v[198:199], s[74:75], v[222:223]
	v_pk_fma_f32 v[204:205], v[200:201], s[74:75], v[222:223]
	v_exp_f32_e32 v206, v206
	v_exp_f32_e32 v207, v207
	v_exp_f32_e32 v208, v208
	v_exp_f32_e32 v209, v209
	v_pk_fma_f32 v[202:203], v[198:199], v[202:203], s[76:77]
	v_pk_fma_f32 v[204:205], v[200:201], v[204:205], s[76:77]
	v_pk_fma_f32 v[202:203], v[198:199], v[202:203], s[72:73]
	v_pk_fma_f32 v[204:205], v[200:201], v[204:205], s[72:73]
	v_pk_mul_f32 v[202:203], v[202:203], v[198:199] neg_lo:[0,1] neg_hi:[0,1]
	v_pk_mul_f32 v[204:205], v[204:205], v[200:201] neg_lo:[0,1] neg_hi:[0,1]
	v_pk_add_f32 v[206:207], s[72:73], v[206:207] neg_lo:[0,1] neg_hi:[0,1]
; __device__ __forceinline__ unsigned pk2(float lo, float hi) { unsigned r; asm("v_cvt_pk_bf16_f32 %0, %1, %2" : "=v"(r) : "v"(lo), "v"(hi)); return r; }
; __device__ __forceinline__ float sigmoidf_(float x) { return __builtin_amdgcn_rcpf(1.0f + __expf(-x)); }
;     __device__ __forceinline__ void operator()(const f32x4 (&acc)[2][2][4][2], const Unit& u, int wr, int wc, int fr, int fq) const {
;     ...
;         for (int ai = 0; ai < 2; ++ai)
; #pragma unroll
;             for (int m = 0; m < 4; ++m) { const size_t off = (size_t)(row0 + ai * HALF + m * 16) * LW + ch0;
;                 float xc[8]; unpack8(xraw[ai][m], xc);
;                 float la[8], uu[8];
; #pragma unroll
;                 for (int n = 0; n < 2; ++n)
; #pragma unroll
;                     for (int j = 0; j < 4; ++j) { const int e = 4 * n + j;
;                         const float r = sigmoidf_(acc[ai][0][m][n][j] + br[e]), ig = sigmoidf_(acc[ai][1][m][n][j] + bi[e]);
;                         const float l = -8.0f * r * sp[e]; la[e] = l;
;                         const float x2 = 2.0f * l;
;                         const float om = x2 > -0.03125f ? -x2 * (1.0f + x2 * (0.5f + x2 * (0.16666667f + x2 * 0.041666668f))) : 1.0f - __expf(x2);
;                         uu[e] = __builtin_amdgcn_sqrtf(om) * (ig * xc[e]); }
;                 u32x4 w0, w1; w0.x = pk2(la[0], uu[0]); w0.y = pk2(la[1], uu[1]); w0.z = pk2(la[2], uu[2]); w0.w = pk2(la[3], uu[3]);
;                 w1.x = pk2(la[4], uu[4]); w1.y = pk2(la[5], uu[5]); w1.z = pk2(la[6], uu[6]); w1.w = pk2(la[7], uu[7]);
;                 *(u32x4*)(LU + off) = w0; *(u32x4*)(LU + off + 4) = w1; }
	v_pk_add_f32 v[208:209], s[72:73], v[208:209] neg_lo:[0,1] neg_hi:[0,1]
	v_cmp_lt_f32_e64 s[78:79], s4, v198
	v_cmp_lt_f32_e64 s[80:81], s4, v199
	v_cmp_lt_f32_e64 s[82:83], s4, v200
	v_cmp_lt_f32_e64 s[24:25], s4, v201
	v_cndmask_b32_e64 v202, v206, v202, s[78:79]
	v_cndmask_b32_e64 v203, v207, v203, s[80:81]
	v_cndmask_b32_e64 v204, v208, v204, s[82:83]
	v_cndmask_b32_e64 v205, v209, v205, s[24:25]
	v_sqrt_f32_e32 v202, v202
	v_sqrt_f32_e32 v203, v203
	v_sqrt_f32_e32 v204, v204
	v_sqrt_f32_e32 v205, v205
	v_pk_mul_f32 v[164:165], v[164:165], v[202:203]
	v_pk_mul_f32 v[166:167], v[166:167], v[204:205]
	v_cvt_pk_bf16_f32 v160, v172, v160
	v_cvt_pk_bf16_f32 v161, v173, v161
	v_cvt_pk_bf16_f32 v162, v174, v162
	v_cvt_pk_bf16_f32 v163, v175, v163
	v_cvt_pk_bf16_f32 v164, v168, v164
	v_cvt_pk_bf16_f32 v165, v169, v165
	v_cvt_pk_bf16_f32 v166, v170, v166
	v_cvt_pk_bf16_f32 v167, v171, v167
	v_mov_b32_e32 v197, v225
	global_store_dwordx4 v197, v[160:163], s[44:45]
	global_store_dwordx4 v197, v[164:167], s[44:45] offset:16
	v_pk_add_f32 v[152:153], v[152:153], v[68:69]
	v_pk_add_f32 v[140:141], v[140:141], v[32:33]
	v_pk_add_f32 v[154:155], v[154:155], v[70:71]
	v_pk_add_f32 v[142:143], v[142:143], v[34:35]
	v_pk_add_f32 v[148:149], v[148:149], v[56:57]
	v_pk_add_f32 v[144:145], v[144:145], v[36:37]
	v_pk_add_f32 v[150:151], v[150:151], v[58:59]
	v_pk_add_f32 v[146:147], v[146:147], v[38:39]
	v_pk_mul_f32 v[152:153], v[152:153], s[68:69]
	v_pk_mul_f32 v[140:141], v[140:141], s[68:69]
	v_pk_mul_f32 v[154:155], v[154:155], s[68:69]
	v_pk_mul_f32 v[142:143], v[142:143], s[68:69]
	v_pk_mul_f32 v[148:149], v[148:149], s[68:69]
	v_pk_mul_f32 v[144:145], v[144:145], s[68:69]
	v_pk_mul_f32 v[150:151], v[150:151], s[68:69]
	v_pk_mul_f32 v[146:147], v[146:147], s[68:69]
	v_exp_f32_e32 v152, v152
	v_exp_f32_e32 v153, v153
	v_exp_f32_e32 v154, v154
	v_exp_f32_e32 v155, v155
	v_exp_f32_e32 v148, v148
	v_exp_f32_e32 v149, v149
	v_exp_f32_e32 v150, v150
	v_exp_f32_e32 v151, v151
	v_exp_f32_e32 v140, v140
	v_exp_f32_e32 v141, v141
	v_exp_f32_e32 v142, v142
	v_exp_f32_e32 v143, v143
	v_exp_f32_e32 v144, v144
	v_exp_f32_e32 v145, v145
	v_exp_f32_e32 v146, v146
	v_exp_f32_e32 v147, v147
	v_pk_add_f32 v[152:153], v[152:153], s[72:73]
	v_pk_add_f32 v[140:141], v[140:141], s[72:73]
	v_pk_add_f32 v[154:155], v[154:155], s[72:73]
	v_pk_add_f32 v[142:143], v[142:143], s[72:73]
	v_pk_add_f32 v[148:149], v[148:149], s[72:73]
	v_pk_add_f32 v[144:145], v[144:145], s[72:73]
	v_pk_add_f32 v[150:151], v[150:151], s[72:73]
	v_pk_add_f32 v[146:147], v[146:147], s[72:73]
	v_rcp_f32_e32 v152, v152
	v_rcp_f32_e32 v153, v153
	v_rcp_f32_e32 v154, v154
	v_rcp_f32_e32 v155, v155
	v_rcp_f32_e32 v148, v148
	v_rcp_f32_e32 v149, v149
	v_rcp_f32_e32 v150, v150
	v_rcp_f32_e32 v151, v151
	v_rcp_f32_e32 v140, v140
	v_rcp_f32_e32 v141, v141
	v_rcp_f32_e32 v142, v142
	v_rcp_f32_e32 v143, v143
	v_rcp_f32_e32 v144, v144
	v_rcp_f32_e32 v145, v145
	v_rcp_f32_e32 v146, v146
	v_rcp_f32_e32 v147, v147
	s_waitcnt vmcnt(8)
	v_lshlrev_b32_e32 v230, 16, v176
	v_and_b32_e32 v231, 0xffff0000, v176
	v_lshlrev_b32_e32 v234, 16, v177
	v_and_b32_e32 v235, 0xffff0000, v177
	v_lshlrev_b32_e32 v236, 16, v178
	v_and_b32_e32 v237, 0xffff0000, v178
	v_lshlrev_b32_e32 v238, 16, v179
	v_and_b32_e32 v239, 0xffff0000, v179
	v_pk_mul_f32 v[152:153], v[64:65], v[152:153]
	v_pk_mul_f32 v[154:155], v[66:67], v[154:155]
	v_pk_mul_f32 v[148:149], v[52:53], v[148:149]
	v_pk_mul_f32 v[150:151], v[54:55], v[150:151]
	v_pk_mul_f32 v[140:141], v[140:141], v[230:231]
	v_pk_mul_f32 v[142:143], v[142:143], v[234:235]
	v_pk_mul_f32 v[144:145], v[144:145], v[236:237]
	v_pk_mul_f32 v[146:147], v[146:147], v[238:239]
	v_pk_add_f32 v[198:199], v[152:153], v[152:153]
	v_pk_add_f32 v[200:201], v[154:155], v[154:155]
	v_pk_mul_f32 v[206:207], v[198:199], s[70:71]
	v_pk_mul_f32 v[208:209], v[200:201], s[70:71]
	v_pk_fma_f32 v[202:203], v[198:199], s[74:75], v[222:223]
	v_pk_fma_f32 v[204:205], v[200:201], s[74:75], v[222:223]
	v_exp_f32_e32 v206, v206
	v_exp_f32_e32 v207, v207
	v_exp_f32_e32 v208, v208
	v_exp_f32_e32 v209, v209
	v_pk_fma_f32 v[202:203], v[198:199], v[202:203], s[76:77]
	v_pk_fma_f32 v[204:205], v[200:201], v[204:205], s[76:77]
	v_pk_fma_f32 v[202:203], v[198:199], v[202:203], s[72:73]
	v_pk_fma_f32 v[204:205], v[200:201], v[204:205], s[72:73]
	v_pk_mul_f32 v[202:203], v[202:203], v[198:199] neg_lo:[0,1] neg_hi:[0,1]
	v_pk_mul_f32 v[204:205], v[204:205], v[200:201] neg_lo:[0,1] neg_hi:[0,1]
	v_pk_add_f32 v[206:207], s[72:73], v[206:207] neg_lo:[0,1] neg_hi:[0,1]
	v_pk_add_f32 v[208:209], s[72:73], v[208:209] neg_lo:[0,1] neg_hi:[0,1]
	v_cmp_lt_f32_e64 s[78:79], s4, v198
	v_cmp_lt_f32_e64 s[80:81], s4, v199
	v_cmp_lt_f32_e64 s[82:83], s4, v200
	v_cmp_lt_f32_e64 s[24:25], s4, v201
	v_cndmask_b32_e64 v202, v206, v202, s[78:79]
	v_cndmask_b32_e64 v203, v207, v203, s[80:81]
	v_cndmask_b32_e64 v204, v208, v204, s[82:83]
	v_cndmask_b32_e64 v205, v209, v205, s[24:25]
	v_sqrt_f32_e32 v202, v202
	v_sqrt_f32_e32 v203, v203
	v_sqrt_f32_e32 v204, v204
	v_sqrt_f32_e32 v205, v205
	v_pk_mul_f32 v[140:141], v[140:141], v[202:203]
	v_pk_mul_f32 v[142:143], v[142:143], v[204:205]
	v_pk_add_f32 v[198:199], v[148:149], v[148:149]
	v_pk_add_f32 v[200:201], v[150:151], v[150:151]
	v_pk_mul_f32 v[206:207], v[198:199], s[70:71]
	v_pk_mul_f32 v[208:209], v[200:201], s[70:71]
	v_pk_fma_f32 v[202:203], v[198:199], s[74:75], v[222:223]
	v_pk_fma_f32 v[204:205], v[200:201], s[74:75], v[222:223]
	v_exp_f32_e32 v206, v206
	v_exp_f32_e32 v207, v207
	v_exp_f32_e32 v208, v208
	v_exp_f32_e32 v209, v209
	v_pk_fma_f32 v[202:203], v[198:199], v[202:203], s[76:77]
; __device__ __forceinline__ unsigned pk2(float lo, float hi) { unsigned r; asm("v_cvt_pk_bf16_f32 %0, %1, %2" : "=v"(r) : "v"(lo), "v"(hi)); return r; }
; __device__ __forceinline__ float sigmoidf_(float x) { return __builtin_amdgcn_rcpf(1.0f + __expf(-x)); }
;     __device__ __forceinline__ void operator()(const f32x4 (&acc)[2][2][4][2], const Unit& u, int wr, int wc, int fr, int fq) const {
;     ...
;         for (int ai = 0; ai < 2; ++ai)
; #pragma unroll
;             for (int m = 0; m < 4; ++m) { const size_t off = (size_t)(row0 + ai * HALF + m * 16) * LW + ch0;
;                 float xc[8]; unpack8(xraw[ai][m], xc);
;                 float la[8], uu[8];
; #pragma unroll
;                 for (int n = 0; n < 2; ++n)
; #pragma unroll
;                     for (int j = 0; j < 4; ++j) { const int e = 4 * n + j;
;                         const float r = sigmoidf_(acc[ai][0][m][n][j] + br[e]), ig = sigmoidf_(acc[ai][1][m][n][j] + bi[e]);
;                         const float l = -8.0f * r * sp[e]; la[e] = l;
;                         const float x2 = 2.0f * l;
;                         const float om = x2 > -0.03125f ? -x2 * (1.0f + x2 * (0.5f + x2 * (0.16666667f + x2 * 0.041666668f))) : 1.0f - __expf(x2);
;                         uu[e] = __builtin_amdgcn_sqrtf(om) * (ig * xc[e]); }
;                 u32x4 w0, w1; w0.x = pk2(la[0], uu[0]); w0.y = pk2(la[1], uu[1]); w0.z = pk2(la[2], uu[2]); w0.w = pk2(la[3], uu[3]);
;                 w1.x = pk2(la[4], uu[4]); w1.y = pk2(la[5], uu[5]); w1.z = pk2(la[6], uu[6]); w1.w = pk2(la[7], uu[7]);
;                 *(u32x4*)(LU + off) = w0; *(u32x4*)(LU + off + 4) = w1; }
	v_pk_fma_f32 v[204:205], v[200:201], v[204:205], s[76:77]
	v_pk_fma_f32 v[202:203], v[198:199], v[202:203], s[72:73]
	v_pk_fma_f32 v[204:205], v[200:201], v[204:205], s[72:73]
	v_pk_mul_f32 v[202:203], v[202:203], v[198:199] neg_lo:[0,1] neg_hi:[0,1]
	v_pk_mul_f32 v[204:205], v[204:205], v[200:201] neg_lo:[0,1] neg_hi:[0,1]
	v_pk_add_f32 v[206:207], s[72:73], v[206:207] neg_lo:[0,1] neg_hi:[0,1]
	v_pk_add_f32 v[208:209], s[72:73], v[208:209] neg_lo:[0,1] neg_hi:[0,1]
	v_cmp_lt_f32_e64 s[78:79], s4, v198
	v_cmp_lt_f32_e64 s[80:81], s4, v199
	v_cmp_lt_f32_e64 s[82:83], s4, v200
	v_cmp_lt_f32_e64 s[24:25], s4, v201
	v_cndmask_b32_e64 v202, v206, v202, s[78:79]
	v_cndmask_b32_e64 v203, v207, v203, s[80:81]
	v_cndmask_b32_e64 v204, v208, v204, s[82:83]
	v_cndmask_b32_e64 v205, v209, v205, s[24:25]
	v_sqrt_f32_e32 v202, v202
	v_sqrt_f32_e32 v203, v203
	v_sqrt_f32_e32 v204, v204
	v_sqrt_f32_e32 v205, v205
	v_pk_mul_f32 v[144:145], v[144:145], v[202:203]
	v_pk_mul_f32 v[146:147], v[146:147], v[204:205]
	v_cvt_pk_bf16_f32 v140, v152, v140
	v_cvt_pk_bf16_f32 v141, v153, v141
	v_cvt_pk_bf16_f32 v142, v154, v142
	v_cvt_pk_bf16_f32 v143, v155, v143
	v_cvt_pk_bf16_f32 v144, v148, v144
	v_cvt_pk_bf16_f32 v145, v149, v145
	v_cvt_pk_bf16_f32 v146, v150, v146
	v_cvt_pk_bf16_f32 v147, v151, v147
	v_add_u32_e32 v197, 0x20000, v225
	global_store_dwordx4 v197, v[140:143], s[44:45]
	global_store_dwordx4 v197, v[144:147], s[44:45] offset:16
	v_pk_add_f32 v[132:133], v[132:133], v[68:69]
	v_pk_add_f32 v[120:121], v[120:121], v[32:33]
	v_pk_add_f32 v[134:135], v[134:135], v[70:71]
	v_pk_add_f32 v[122:123], v[122:123], v[34:35]
	v_pk_add_f32 v[128:129], v[128:129], v[56:57]
	v_pk_add_f32 v[124:125], v[124:125], v[36:37]
	v_pk_add_f32 v[130:131], v[130:131], v[58:59]
	v_pk_add_f32 v[126:127], v[126:127], v[38:39]
	v_pk_mul_f32 v[132:133], v[132:133], s[68:69]
	v_pk_mul_f32 v[120:121], v[120:121], s[68:69]
	v_pk_mul_f32 v[134:135], v[134:135], s[68:69]
	v_pk_mul_f32 v[122:123], v[122:123], s[68:69]
	v_pk_mul_f32 v[128:129], v[128:129], s[68:69]
	v_pk_mul_f32 v[124:125], v[124:125], s[68:69]
	v_pk_mul_f32 v[130:131], v[130:131], s[68:69]
	v_pk_mul_f32 v[126:127], v[126:127], s[68:69]
	v_exp_f32_e32 v132, v132
	v_exp_f32_e32 v133, v133
	v_exp_f32_e32 v134, v134
	v_exp_f32_e32 v135, v135
	v_exp_f32_e32 v128, v128
	v_exp_f32_e32 v129, v129
	v_exp_f32_e32 v130, v130
	v_exp_f32_e32 v131, v131
	v_exp_f32_e32 v120, v120
	v_exp_f32_e32 v121, v121
	v_exp_f32_e32 v122, v122
	v_exp_f32_e32 v123, v123
	v_exp_f32_e32 v124, v124
	v_exp_f32_e32 v125, v125
	v_exp_f32_e32 v126, v126
	v_exp_f32_e32 v127, v127
	v_pk_add_f32 v[132:133], v[132:133], s[72:73]
	v_pk_add_f32 v[120:121], v[120:121], s[72:73]
	v_pk_add_f32 v[134:135], v[134:135], s[72:73]
	v_pk_add_f32 v[122:123], v[122:123], s[72:73]
	v_pk_add_f32 v[128:129], v[128:129], s[72:73]
	v_pk_add_f32 v[124:125], v[124:125], s[72:73]
	v_pk_add_f32 v[130:131], v[130:131], s[72:73]
	v_pk_add_f32 v[126:127], v[126:127], s[72:73]
	v_rcp_f32_e32 v132, v132
	v_rcp_f32_e32 v133, v133
	v_rcp_f32_e32 v134, v134
	v_rcp_f32_e32 v135, v135
	v_rcp_f32_e32 v128, v128
	v_rcp_f32_e32 v129, v129
	v_rcp_f32_e32 v130, v130
	v_rcp_f32_e32 v131, v131
	v_rcp_f32_e32 v120, v120
	v_rcp_f32_e32 v121, v121
	v_rcp_f32_e32 v122, v122
	v_rcp_f32_e32 v123, v123
	v_rcp_f32_e32 v124, v124
	v_rcp_f32_e32 v125, v125
	v_rcp_f32_e32 v126, v126
	v_rcp_f32_e32 v127, v127
	s_waitcnt vmcnt(9)
	v_lshlrev_b32_e32 v230, 16, v156
	v_and_b32_e32 v231, 0xffff0000, v156
	v_lshlrev_b32_e32 v234, 16, v157
	v_and_b32_e32 v235, 0xffff0000, v157
	v_lshlrev_b32_e32 v236, 16, v158
	v_and_b32_e32 v237, 0xffff0000, v158
	v_lshlrev_b32_e32 v238, 16, v159
	v_and_b32_e32 v239, 0xffff0000, v159
	v_pk_mul_f32 v[132:133], v[64:65], v[132:133]
	v_pk_mul_f32 v[134:135], v[66:67], v[134:135]
	v_pk_mul_f32 v[128:129], v[52:53], v[128:129]
	v_pk_mul_f32 v[130:131], v[54:55], v[130:131]
	v_pk_mul_f32 v[120:121], v[120:121], v[230:231]
	v_pk_mul_f32 v[122:123], v[122:123], v[234:235]
	v_pk_mul_f32 v[124:125], v[124:125], v[236:237]
	v_pk_mul_f32 v[126:127], v[126:127], v[238:239]
	v_pk_add_f32 v[198:199], v[132:133], v[132:133]
	v_pk_add_f32 v[200:201], v[134:135], v[134:135]
	v_pk_mul_f32 v[206:207], v[198:199], s[70:71]
	v_pk_mul_f32 v[208:209], v[200:201], s[70:71]
	v_pk_fma_f32 v[202:203], v[198:199], s[74:75], v[222:223]
	v_pk_fma_f32 v[204:205], v[200:201], s[74:75], v[222:223]
	v_exp_f32_e32 v206, v206
	v_exp_f32_e32 v207, v207
	v_exp_f32_e32 v208, v208
	v_exp_f32_e32 v209, v209
	v_pk_fma_f32 v[202:203], v[198:199], v[202:203], s[76:77]
	v_pk_fma_f32 v[204:205], v[200:201], v[204:205], s[76:77]
	v_pk_fma_f32 v[202:203], v[198:199], v[202:203], s[72:73]
	v_pk_fma_f32 v[204:205], v[200:201], v[204:205], s[72:73]
	v_pk_mul_f32 v[202:203], v[202:203], v[198:199] neg_lo:[0,1] neg_hi:[0,1]
	v_pk_mul_f32 v[204:205], v[204:205], v[200:201] neg_lo:[0,1] neg_hi:[0,1]
	v_pk_add_f32 v[206:207], s[72:73], v[206:207] neg_lo:[0,1] neg_hi:[0,1]
	v_pk_add_f32 v[208:209], s[72:73], v[208:209] neg_lo:[0,1] neg_hi:[0,1]
	v_cmp_lt_f32_e64 s[78:79], s4, v198
	v_cmp_lt_f32_e64 s[80:81], s4, v199
	v_cmp_lt_f32_e64 s[82:83], s4, v200
	v_cmp_lt_f32_e64 s[24:25], s4, v201
	v_cndmask_b32_e64 v202, v206, v202, s[78:79]
	v_cndmask_b32_e64 v203, v207, v203, s[80:81]
	v_cndmask_b32_e64 v204, v208, v204, s[82:83]
	v_cndmask_b32_e64 v205, v209, v205, s[24:25]
	v_sqrt_f32_e32 v202, v202
	v_sqrt_f32_e32 v203, v203
	v_sqrt_f32_e32 v204, v204
	v_sqrt_f32_e32 v205, v205
	v_pk_mul_f32 v[120:121], v[120:121], v[202:203]
	v_pk_mul_f32 v[122:123], v[122:123], v[204:205]
	v_pk_add_f32 v[198:199], v[128:129], v[128:129]
; __device__ __forceinline__ unsigned pk2(float lo, float hi) { unsigned r; asm("v_cvt_pk_bf16_f32 %0, %1, %2" : "=v"(r) : "v"(lo), "v"(hi)); return r; }
; __device__ __forceinline__ float sigmoidf_(float x) { return __builtin_amdgcn_rcpf(1.0f + __expf(-x)); }
;     __device__ __forceinline__ void operator()(const f32x4 (&acc)[2][2][4][2], const Unit& u, int wr, int wc, int fr, int fq) const {
;     ...
;         for (int ai = 0; ai < 2; ++ai)
; #pragma unroll
;             for (int m = 0; m < 4; ++m) { const size_t off = (size_t)(row0 + ai * HALF + m * 16) * LW + ch0;
;                 float xc[8]; unpack8(xraw[ai][m], xc);
;                 float la[8], uu[8];
; #pragma unroll
;                 for (int n = 0; n < 2; ++n)
; #pragma unroll
;                     for (int j = 0; j < 4; ++j) { const int e = 4 * n + j;
;                         const float r = sigmoidf_(acc[ai][0][m][n][j] + br[e]), ig = sigmoidf_(acc[ai][1][m][n][j] + bi[e]);
;                         const float l = -8.0f * r * sp[e]; la[e] = l;
;                         const float x2 = 2.0f * l;
;                         const float om = x2 > -0.03125f ? -x2 * (1.0f + x2 * (0.5f + x2 * (0.16666667f + x2 * 0.041666668f))) : 1.0f - __expf(x2);
;                         uu[e] = __builtin_amdgcn_sqrtf(om) * (ig * xc[e]); }
;                 u32x4 w0, w1; w0.x = pk2(la[0], uu[0]); w0.y = pk2(la[1], uu[1]); w0.z = pk2(la[2], uu[2]); w0.w = pk2(la[3], uu[3]);
;                 w1.x = pk2(la[4], uu[4]); w1.y = pk2(la[5], uu[5]); w1.z = pk2(la[6], uu[6]); w1.w = pk2(la[7], uu[7]);
;                 *(u32x4*)(LU + off) = w0; *(u32x4*)(LU + off + 4) = w1; }
	v_pk_add_f32 v[200:201], v[130:131], v[130:131]
	v_pk_mul_f32 v[206:207], v[198:199], s[70:71]
	v_pk_mul_f32 v[208:209], v[200:201], s[70:71]
	v_pk_fma_f32 v[202:203], v[198:199], s[74:75], v[222:223]
	v_pk_fma_f32 v[204:205], v[200:201], s[74:75], v[222:223]
	v_exp_f32_e32 v206, v206
	v_exp_f32_e32 v207, v207
	v_exp_f32_e32 v208, v208
	v_exp_f32_e32 v209, v209
	v_pk_fma_f32 v[202:203], v[198:199], v[202:203], s[76:77]
	v_pk_fma_f32 v[204:205], v[200:201], v[204:205], s[76:77]
	v_pk_fma_f32 v[202:203], v[198:199], v[202:203], s[72:73]
	v_pk_fma_f32 v[204:205], v[200:201], v[204:205], s[72:73]
	v_pk_mul_f32 v[202:203], v[202:203], v[198:199] neg_lo:[0,1] neg_hi:[0,1]
	v_pk_mul_f32 v[204:205], v[204:205], v[200:201] neg_lo:[0,1] neg_hi:[0,1]
	v_pk_add_f32 v[206:207], s[72:73], v[206:207] neg_lo:[0,1] neg_hi:[0,1]
	v_pk_add_f32 v[208:209], s[72:73], v[208:209] neg_lo:[0,1] neg_hi:[0,1]
	v_cmp_lt_f32_e64 s[78:79], s4, v198
	v_cmp_lt_f32_e64 s[80:81], s4, v199
	v_cmp_lt_f32_e64 s[82:83], s4, v200
	v_cmp_lt_f32_e64 s[24:25], s4, v201
	v_cndmask_b32_e64 v202, v206, v202, s[78:79]
	v_cndmask_b32_e64 v203, v207, v203, s[80:81]
	v_cndmask_b32_e64 v204, v208, v204, s[82:83]
	v_cndmask_b32_e64 v205, v209, v205, s[24:25]
	v_sqrt_f32_e32 v202, v202
	v_sqrt_f32_e32 v203, v203
	v_sqrt_f32_e32 v204, v204
	v_sqrt_f32_e32 v205, v205
	v_pk_mul_f32 v[124:125], v[124:125], v[202:203]
	v_pk_mul_f32 v[126:127], v[126:127], v[204:205]
	v_cvt_pk_bf16_f32 v120, v132, v120
	v_cvt_pk_bf16_f32 v121, v133, v121
	v_cvt_pk_bf16_f32 v122, v134, v122
	v_cvt_pk_bf16_f32 v123, v135, v123
	v_cvt_pk_bf16_f32 v124, v128, v124
	v_cvt_pk_bf16_f32 v125, v129, v125
	v_cvt_pk_bf16_f32 v126, v130, v126
	v_cvt_pk_bf16_f32 v127, v131, v127
	v_add_u32_e32 v197, 0x40000, v225
	global_store_dwordx4 v197, v[120:123], s[44:45]
	global_store_dwordx4 v197, v[124:127], s[44:45] offset:16
	v_pk_add_f32 v[112:113], v[112:113], v[68:69]
	v_pk_add_f32 v[100:101], v[100:101], v[32:33]
	v_pk_add_f32 v[114:115], v[114:115], v[70:71]
	v_pk_add_f32 v[102:103], v[102:103], v[34:35]
	v_pk_add_f32 v[108:109], v[108:109], v[56:57]
	v_pk_add_f32 v[104:105], v[104:105], v[36:37]
	v_pk_add_f32 v[110:111], v[110:111], v[58:59]
	v_pk_add_f32 v[106:107], v[106:107], v[38:39]
	v_pk_mul_f32 v[112:113], v[112:113], s[68:69]
	v_pk_mul_f32 v[100:101], v[100:101], s[68:69]
	v_pk_mul_f32 v[114:115], v[114:115], s[68:69]
	v_pk_mul_f32 v[102:103], v[102:103], s[68:69]
	v_pk_mul_f32 v[108:109], v[108:109], s[68:69]
	v_pk_mul_f32 v[104:105], v[104:105], s[68:69]
	v_pk_mul_f32 v[110:111], v[110:111], s[68:69]
	v_pk_mul_f32 v[106:107], v[106:107], s[68:69]
	v_exp_f32_e32 v112, v112
	v_exp_f32_e32 v113, v113
	v_exp_f32_e32 v114, v114
	v_exp_f32_e32 v115, v115
	v_exp_f32_e32 v108, v108
	v_exp_f32_e32 v109, v109
	v_exp_f32_e32 v110, v110
	v_exp_f32_e32 v111, v111
	v_exp_f32_e32 v100, v100
	v_exp_f32_e32 v101, v101
	v_exp_f32_e32 v102, v102
	v_exp_f32_e32 v103, v103
	v_exp_f32_e32 v104, v104
	v_exp_f32_e32 v105, v105
	v_exp_f32_e32 v106, v106
	v_exp_f32_e32 v107, v107
	v_pk_add_f32 v[112:113], v[112:113], s[72:73]
	v_pk_add_f32 v[100:101], v[100:101], s[72:73]
	v_pk_add_f32 v[114:115], v[114:115], s[72:73]
	v_pk_add_f32 v[102:103], v[102:103], s[72:73]
	v_pk_add_f32 v[108:109], v[108:109], s[72:73]
	v_pk_add_f32 v[104:105], v[104:105], s[72:73]
	v_pk_add_f32 v[110:111], v[110:111], s[72:73]
	v_pk_add_f32 v[106:107], v[106:107], s[72:73]
	v_rcp_f32_e32 v112, v112
	v_rcp_f32_e32 v113, v113
	v_rcp_f32_e32 v114, v114
	v_rcp_f32_e32 v115, v115
	v_rcp_f32_e32 v108, v108
	v_rcp_f32_e32 v109, v109
	v_rcp_f32_e32 v110, v110
	v_rcp_f32_e32 v111, v111
	v_rcp_f32_e32 v100, v100
	v_rcp_f32_e32 v101, v101
	v_rcp_f32_e32 v102, v102
	v_rcp_f32_e32 v103, v103
	v_rcp_f32_e32 v104, v104
	v_rcp_f32_e32 v105, v105
	v_rcp_f32_e32 v106, v106
	v_rcp_f32_e32 v107, v107
	s_waitcnt vmcnt(10)
	v_lshlrev_b32_e32 v230, 16, v136
	v_and_b32_e32 v231, 0xffff0000, v136
	v_lshlrev_b32_e32 v234, 16, v137
	v_and_b32_e32 v235, 0xffff0000, v137
	v_lshlrev_b32_e32 v236, 16, v138
	v_and_b32_e32 v237, 0xffff0000, v138
	v_lshlrev_b32_e32 v238, 16, v139
	v_and_b32_e32 v239, 0xffff0000, v139
	v_pk_mul_f32 v[112:113], v[64:65], v[112:113]
	v_pk_mul_f32 v[114:115], v[66:67], v[114:115]
	v_pk_mul_f32 v[108:109], v[52:53], v[108:109]
	v_pk_mul_f32 v[110:111], v[54:55], v[110:111]
	v_pk_mul_f32 v[100:101], v[100:101], v[230:231]
	v_pk_mul_f32 v[102:103], v[102:103], v[234:235]
	v_pk_mul_f32 v[104:105], v[104:105], v[236:237]
	v_pk_mul_f32 v[106:107], v[106:107], v[238:239]
	v_pk_add_f32 v[198:199], v[112:113], v[112:113]
	v_pk_add_f32 v[200:201], v[114:115], v[114:115]
	v_pk_mul_f32 v[206:207], v[198:199], s[70:71]
	v_pk_mul_f32 v[208:209], v[200:201], s[70:71]
	v_pk_fma_f32 v[202:203], v[198:199], s[74:75], v[222:223]
	v_pk_fma_f32 v[204:205], v[200:201], s[74:75], v[222:223]
	v_exp_f32_e32 v206, v206
	v_exp_f32_e32 v207, v207
	v_exp_f32_e32 v208, v208
	v_exp_f32_e32 v209, v209
	v_pk_fma_f32 v[202:203], v[198:199], v[202:203], s[76:77]
	v_pk_fma_f32 v[204:205], v[200:201], v[204:205], s[76:77]
	v_pk_fma_f32 v[202:203], v[198:199], v[202:203], s[72:73]
	v_pk_fma_f32 v[204:205], v[200:201], v[204:205], s[72:73]
	v_pk_mul_f32 v[202:203], v[202:203], v[198:199] neg_lo:[0,1] neg_hi:[0,1]
	v_pk_mul_f32 v[204:205], v[204:205], v[200:201] neg_lo:[0,1] neg_hi:[0,1]
	v_pk_add_f32 v[206:207], s[72:73], v[206:207] neg_lo:[0,1] neg_hi:[0,1]
	v_pk_add_f32 v[208:209], s[72:73], v[208:209] neg_lo:[0,1] neg_hi:[0,1]
	v_cmp_lt_f32_e64 s[78:79], s4, v198
	v_cmp_lt_f32_e64 s[80:81], s4, v199
	v_cmp_lt_f32_e64 s[82:83], s4, v200
	v_cmp_lt_f32_e64 s[24:25], s4, v201
	v_cndmask_b32_e64 v202, v206, v202, s[78:79]
; __device__ __forceinline__ unsigned pk2(float lo, float hi) { unsigned r; asm("v_cvt_pk_bf16_f32 %0, %1, %2" : "=v"(r) : "v"(lo), "v"(hi)); return r; }
; __device__ __forceinline__ float sigmoidf_(float x) { return __builtin_amdgcn_rcpf(1.0f + __expf(-x)); }
;     __device__ __forceinline__ void operator()(const f32x4 (&acc)[2][2][4][2], const Unit& u, int wr, int wc, int fr, int fq) const {
;     ...
;         for (int ai = 0; ai < 2; ++ai)
; #pragma unroll
;             for (int m = 0; m < 4; ++m) { const size_t off = (size_t)(row0 + ai * HALF + m * 16) * LW + ch0;
;                 float xc[8]; unpack8(xraw[ai][m], xc);
;                 float la[8], uu[8];
; #pragma unroll
;                 for (int n = 0; n < 2; ++n)
; #pragma unroll
;                     for (int j = 0; j < 4; ++j) { const int e = 4 * n + j;
;                         const float r = sigmoidf_(acc[ai][0][m][n][j] + br[e]), ig = sigmoidf_(acc[ai][1][m][n][j] + bi[e]);
;                         const float l = -8.0f * r * sp[e]; la[e] = l;
;                         const float x2 = 2.0f * l;
;                         const float om = x2 > -0.03125f ? -x2 * (1.0f + x2 * (0.5f + x2 * (0.16666667f + x2 * 0.041666668f))) : 1.0f - __expf(x2);
;                         uu[e] = __builtin_amdgcn_sqrtf(om) * (ig * xc[e]); }
;                 u32x4 w0, w1; w0.x = pk2(la[0], uu[0]); w0.y = pk2(la[1], uu[1]); w0.z = pk2(la[2], uu[2]); w0.w = pk2(la[3], uu[3]);
;                 w1.x = pk2(la[4], uu[4]); w1.y = pk2(la[5], uu[5]); w1.z = pk2(la[6], uu[6]); w1.w = pk2(la[7], uu[7]);
;                 *(u32x4*)(LU + off) = w0; *(u32x4*)(LU + off + 4) = w1; }
	v_cndmask_b32_e64 v203, v207, v203, s[80:81]
	v_cndmask_b32_e64 v204, v208, v204, s[82:83]
	v_cndmask_b32_e64 v205, v209, v205, s[24:25]
	v_sqrt_f32_e32 v202, v202
	v_sqrt_f32_e32 v203, v203
	v_sqrt_f32_e32 v204, v204
	v_sqrt_f32_e32 v205, v205
	v_pk_mul_f32 v[100:101], v[100:101], v[202:203]
	v_pk_mul_f32 v[102:103], v[102:103], v[204:205]
	v_pk_add_f32 v[198:199], v[108:109], v[108:109]
	v_pk_add_f32 v[200:201], v[110:111], v[110:111]
	v_pk_mul_f32 v[206:207], v[198:199], s[70:71]
	v_pk_mul_f32 v[208:209], v[200:201], s[70:71]
	v_pk_fma_f32 v[202:203], v[198:199], s[74:75], v[222:223]
	v_pk_fma_f32 v[204:205], v[200:201], s[74:75], v[222:223]
	v_exp_f32_e32 v206, v206
	v_exp_f32_e32 v207, v207
	v_exp_f32_e32 v208, v208
	v_exp_f32_e32 v209, v209
	v_pk_fma_f32 v[202:203], v[198:199], v[202:203], s[76:77]
	v_pk_fma_f32 v[204:205], v[200:201], v[204:205], s[76:77]
	v_pk_fma_f32 v[202:203], v[198:199], v[202:203], s[72:73]
	v_pk_fma_f32 v[204:205], v[200:201], v[204:205], s[72:73]
	v_pk_mul_f32 v[202:203], v[202:203], v[198:199] neg_lo:[0,1] neg_hi:[0,1]
	v_pk_mul_f32 v[204:205], v[204:205], v[200:201] neg_lo:[0,1] neg_hi:[0,1]
	v_pk_add_f32 v[206:207], s[72:73], v[206:207] neg_lo:[0,1] neg_hi:[0,1]
	v_pk_add_f32 v[208:209], s[72:73], v[208:209] neg_lo:[0,1] neg_hi:[0,1]
	v_cmp_lt_f32_e64 s[78:79], s4, v198
	v_cmp_lt_f32_e64 s[80:81], s4, v199
	v_cmp_lt_f32_e64 s[82:83], s4, v200
	v_cmp_lt_f32_e64 s[24:25], s4, v201
	v_cndmask_b32_e64 v202, v206, v202, s[78:79]
	v_cndmask_b32_e64 v203, v207, v203, s[80:81]
	v_cndmask_b32_e64 v204, v208, v204, s[82:83]
	v_cndmask_b32_e64 v205, v209, v205, s[24:25]
	v_sqrt_f32_e32 v202, v202
	v_sqrt_f32_e32 v203, v203
	v_sqrt_f32_e32 v204, v204
	v_sqrt_f32_e32 v205, v205
	v_pk_mul_f32 v[104:105], v[104:105], v[202:203]
	v_pk_mul_f32 v[106:107], v[106:107], v[204:205]
	v_cvt_pk_bf16_f32 v100, v112, v100
	v_cvt_pk_bf16_f32 v101, v113, v101
	v_cvt_pk_bf16_f32 v102, v114, v102
	v_cvt_pk_bf16_f32 v103, v115, v103
	v_cvt_pk_bf16_f32 v104, v108, v104
	v_cvt_pk_bf16_f32 v105, v109, v105
	v_cvt_pk_bf16_f32 v106, v110, v106
	v_cvt_pk_bf16_f32 v107, v111, v107
	v_add_u32_e32 v197, 0x60000, v225
	global_store_dwordx4 v197, v[100:103], s[44:45]
	global_store_dwordx4 v197, v[104:107], s[44:45] offset:16
	v_pk_add_f32 v[92:93], v[92:93], v[68:69]
	v_pk_add_f32 v[80:81], v[80:81], v[32:33]
	v_pk_add_f32 v[94:95], v[94:95], v[70:71]
	v_pk_add_f32 v[82:83], v[82:83], v[34:35]
	v_pk_add_f32 v[88:89], v[88:89], v[56:57]
	v_pk_add_f32 v[84:85], v[84:85], v[36:37]
	v_pk_add_f32 v[90:91], v[90:91], v[58:59]
	v_pk_add_f32 v[86:87], v[86:87], v[38:39]
	v_pk_mul_f32 v[92:93], v[92:93], s[68:69]
	v_pk_mul_f32 v[80:81], v[80:81], s[68:69]
	v_pk_mul_f32 v[94:95], v[94:95], s[68:69]
	v_pk_mul_f32 v[82:83], v[82:83], s[68:69]
	v_pk_mul_f32 v[88:89], v[88:89], s[68:69]
	v_pk_mul_f32 v[84:85], v[84:85], s[68:69]
	v_pk_mul_f32 v[90:91], v[90:91], s[68:69]
	v_pk_mul_f32 v[86:87], v[86:87], s[68:69]
	v_exp_f32_e32 v92, v92
	v_exp_f32_e32 v93, v93
	v_exp_f32_e32 v94, v94
	v_exp_f32_e32 v95, v95
	v_exp_f32_e32 v88, v88
	v_exp_f32_e32 v89, v89
	v_exp_f32_e32 v90, v90
	v_exp_f32_e32 v91, v91
	v_exp_f32_e32 v80, v80
	v_exp_f32_e32 v81, v81
	v_exp_f32_e32 v82, v82
	v_exp_f32_e32 v83, v83
	v_exp_f32_e32 v84, v84
	v_exp_f32_e32 v85, v85
	v_exp_f32_e32 v86, v86
	v_exp_f32_e32 v87, v87
	v_pk_add_f32 v[92:93], v[92:93], s[72:73]
	v_pk_add_f32 v[80:81], v[80:81], s[72:73]
	v_pk_add_f32 v[94:95], v[94:95], s[72:73]
	v_pk_add_f32 v[82:83], v[82:83], s[72:73]
	v_pk_add_f32 v[88:89], v[88:89], s[72:73]
	v_pk_add_f32 v[84:85], v[84:85], s[72:73]
	v_pk_add_f32 v[90:91], v[90:91], s[72:73]
	v_pk_add_f32 v[86:87], v[86:87], s[72:73]
	v_rcp_f32_e32 v92, v92
	v_rcp_f32_e32 v93, v93
	v_rcp_f32_e32 v94, v94
	v_rcp_f32_e32 v95, v95
	v_rcp_f32_e32 v88, v88
	v_rcp_f32_e32 v89, v89
	v_rcp_f32_e32 v90, v90
	v_rcp_f32_e32 v91, v91
	v_rcp_f32_e32 v80, v80
	v_rcp_f32_e32 v81, v81
	v_rcp_f32_e32 v82, v82
	v_rcp_f32_e32 v83, v83
	v_rcp_f32_e32 v84, v84
	v_rcp_f32_e32 v85, v85
	v_rcp_f32_e32 v86, v86
	v_rcp_f32_e32 v87, v87
	s_waitcnt vmcnt(11)
	v_lshlrev_b32_e32 v230, 16, v116
	v_and_b32_e32 v231, 0xffff0000, v116
	v_lshlrev_b32_e32 v234, 16, v117
	v_and_b32_e32 v235, 0xffff0000, v117
	v_lshlrev_b32_e32 v236, 16, v118
	v_and_b32_e32 v237, 0xffff0000, v118
	v_lshlrev_b32_e32 v238, 16, v119
	v_and_b32_e32 v239, 0xffff0000, v119
	v_pk_mul_f32 v[92:93], v[64:65], v[92:93]
	v_pk_mul_f32 v[94:95], v[66:67], v[94:95]
	v_pk_mul_f32 v[88:89], v[52:53], v[88:89]
	v_pk_mul_f32 v[90:91], v[54:55], v[90:91]
	v_pk_mul_f32 v[80:81], v[80:81], v[230:231]
	v_pk_mul_f32 v[82:83], v[82:83], v[234:235]
	v_pk_mul_f32 v[84:85], v[84:85], v[236:237]
	v_pk_mul_f32 v[86:87], v[86:87], v[238:239]
	v_pk_add_f32 v[198:199], v[92:93], v[92:93]
	v_pk_add_f32 v[200:201], v[94:95], v[94:95]
	v_pk_mul_f32 v[206:207], v[198:199], s[70:71]
	v_pk_mul_f32 v[208:209], v[200:201], s[70:71]
	v_pk_fma_f32 v[202:203], v[198:199], s[74:75], v[222:223]
	v_pk_fma_f32 v[204:205], v[200:201], s[74:75], v[222:223]
	v_exp_f32_e32 v206, v206
	v_exp_f32_e32 v207, v207
	v_exp_f32_e32 v208, v208
	v_exp_f32_e32 v209, v209
	v_pk_fma_f32 v[202:203], v[198:199], v[202:203], s[76:77]
	v_pk_fma_f32 v[204:205], v[200:201], v[204:205], s[76:77]
	v_pk_fma_f32 v[202:203], v[198:199], v[202:203], s[72:73]
	v_pk_fma_f32 v[204:205], v[200:201], v[204:205], s[72:73]
	v_pk_mul_f32 v[202:203], v[202:203], v[198:199] neg_lo:[0,1] neg_hi:[0,1]
	v_pk_mul_f32 v[204:205], v[204:205], v[200:201] neg_lo:[0,1] neg_hi:[0,1]
	v_pk_add_f32 v[206:207], s[72:73], v[206:207] neg_lo:[0,1] neg_hi:[0,1]
	v_pk_add_f32 v[208:209], s[72:73], v[208:209] neg_lo:[0,1] neg_hi:[0,1]
; __device__ __forceinline__ unsigned pk2(float lo, float hi) { unsigned r; asm("v_cvt_pk_bf16_f32 %0, %1, %2" : "=v"(r) : "v"(lo), "v"(hi)); return r; }
; __device__ __forceinline__ float sigmoidf_(float x) { return __builtin_amdgcn_rcpf(1.0f + __expf(-x)); }
;     __device__ __forceinline__ void operator()(const f32x4 (&acc)[2][2][4][2], const Unit& u, int wr, int wc, int fr, int fq) const {
;     ...
;         for (int ai = 0; ai < 2; ++ai)
; #pragma unroll
;             for (int m = 0; m < 4; ++m) { const size_t off = (size_t)(row0 + ai * HALF + m * 16) * LW + ch0;
;                 float xc[8]; unpack8(xraw[ai][m], xc);
;                 float la[8], uu[8];
; #pragma unroll
;                 for (int n = 0; n < 2; ++n)
; #pragma unroll
;                     for (int j = 0; j < 4; ++j) { const int e = 4 * n + j;
;                         const float r = sigmoidf_(acc[ai][0][m][n][j] + br[e]), ig = sigmoidf_(acc[ai][1][m][n][j] + bi[e]);
;                         const float l = -8.0f * r * sp[e]; la[e] = l;
;                         const float x2 = 2.0f * l;
;                         const float om = x2 > -0.03125f ? -x2 * (1.0f + x2 * (0.5f + x2 * (0.16666667f + x2 * 0.041666668f))) : 1.0f - __expf(x2);
;                         uu[e] = __builtin_amdgcn_sqrtf(om) * (ig * xc[e]); }
;                 u32x4 w0, w1; w0.x = pk2(la[0], uu[0]); w0.y = pk2(la[1], uu[1]); w0.z = pk2(la[2], uu[2]); w0.w = pk2(la[3], uu[3]);
;                 w1.x = pk2(la[4], uu[4]); w1.y = pk2(la[5], uu[5]); w1.z = pk2(la[6], uu[6]); w1.w = pk2(la[7], uu[7]);
;                 *(u32x4*)(LU + off) = w0; *(u32x4*)(LU + off + 4) = w1; }
	v_cmp_lt_f32_e64 s[78:79], s4, v198
	v_cmp_lt_f32_e64 s[80:81], s4, v199
	v_cmp_lt_f32_e64 s[82:83], s4, v200
	v_cmp_lt_f32_e64 s[24:25], s4, v201
	v_cndmask_b32_e64 v202, v206, v202, s[78:79]
	v_cndmask_b32_e64 v203, v207, v203, s[80:81]
	v_cndmask_b32_e64 v204, v208, v204, s[82:83]
	v_cndmask_b32_e64 v205, v209, v205, s[24:25]
	v_sqrt_f32_e32 v202, v202
	v_sqrt_f32_e32 v203, v203
	v_sqrt_f32_e32 v204, v204
	v_sqrt_f32_e32 v205, v205
	v_pk_mul_f32 v[80:81], v[80:81], v[202:203]
	v_pk_mul_f32 v[82:83], v[82:83], v[204:205]
	v_pk_add_f32 v[198:199], v[88:89], v[88:89]
	v_pk_add_f32 v[200:201], v[90:91], v[90:91]
	v_pk_mul_f32 v[206:207], v[198:199], s[70:71]
	v_pk_mul_f32 v[208:209], v[200:201], s[70:71]
	v_pk_fma_f32 v[202:203], v[198:199], s[74:75], v[222:223]
	v_pk_fma_f32 v[204:205], v[200:201], s[74:75], v[222:223]
	v_exp_f32_e32 v206, v206
	v_exp_f32_e32 v207, v207
	v_exp_f32_e32 v208, v208
	v_exp_f32_e32 v209, v209
	v_pk_fma_f32 v[202:203], v[198:199], v[202:203], s[76:77]
	v_pk_fma_f32 v[204:205], v[200:201], v[204:205], s[76:77]
	v_pk_fma_f32 v[202:203], v[198:199], v[202:203], s[72:73]
	v_pk_fma_f32 v[204:205], v[200:201], v[204:205], s[72:73]
	v_pk_mul_f32 v[202:203], v[202:203], v[198:199] neg_lo:[0,1] neg_hi:[0,1]
	v_pk_mul_f32 v[204:205], v[204:205], v[200:201] neg_lo:[0,1] neg_hi:[0,1]
	v_pk_add_f32 v[206:207], s[72:73], v[206:207] neg_lo:[0,1] neg_hi:[0,1]
	v_pk_add_f32 v[208:209], s[72:73], v[208:209] neg_lo:[0,1] neg_hi:[0,1]
	v_cmp_lt_f32_e64 s[78:79], s4, v198
	v_cmp_lt_f32_e64 s[80:81], s4, v199
	v_cmp_lt_f32_e64 s[82:83], s4, v200
	v_cmp_lt_f32_e64 s[24:25], s4, v201
	v_cndmask_b32_e64 v202, v206, v202, s[78:79]
	v_cndmask_b32_e64 v203, v207, v203, s[80:81]
	v_cndmask_b32_e64 v204, v208, v204, s[82:83]
	v_cndmask_b32_e64 v205, v209, v205, s[24:25]
	v_sqrt_f32_e32 v202, v202
	v_sqrt_f32_e32 v203, v203
	v_sqrt_f32_e32 v204, v204
	v_sqrt_f32_e32 v205, v205
	v_pk_mul_f32 v[84:85], v[84:85], v[202:203]
	v_pk_mul_f32 v[86:87], v[86:87], v[204:205]
	v_cvt_pk_bf16_f32 v80, v92, v80
	v_cvt_pk_bf16_f32 v81, v93, v81
	v_cvt_pk_bf16_f32 v82, v94, v82
	v_cvt_pk_bf16_f32 v83, v95, v83
	v_cvt_pk_bf16_f32 v84, v88, v84
	v_cvt_pk_bf16_f32 v85, v89, v85
	v_cvt_pk_bf16_f32 v86, v90, v86
	v_cvt_pk_bf16_f32 v87, v91, v87
	v_add_u32_e32 v197, 0x100000, v225
	global_store_dwordx4 v197, v[80:83], s[44:45]
	global_store_dwordx4 v197, v[84:87], s[44:45] offset:16
	v_pk_add_f32 v[72:73], v[72:73], v[68:69]
	v_pk_add_f32 v[40:41], v[40:41], v[32:33]
	v_pk_add_f32 v[74:75], v[74:75], v[70:71]
	v_pk_add_f32 v[42:43], v[42:43], v[34:35]
	v_pk_add_f32 v[60:61], v[60:61], v[56:57]
	v_pk_add_f32 v[44:45], v[44:45], v[36:37]
	v_pk_add_f32 v[62:63], v[62:63], v[58:59]
	v_pk_add_f32 v[46:47], v[46:47], v[38:39]
	v_pk_mul_f32 v[72:73], v[72:73], s[68:69]
	v_pk_mul_f32 v[40:41], v[40:41], s[68:69]
	v_pk_mul_f32 v[74:75], v[74:75], s[68:69]
	v_pk_mul_f32 v[42:43], v[42:43], s[68:69]
	v_pk_mul_f32 v[60:61], v[60:61], s[68:69]
	v_pk_mul_f32 v[44:45], v[44:45], s[68:69]
	v_pk_mul_f32 v[62:63], v[62:63], s[68:69]
	v_pk_mul_f32 v[46:47], v[46:47], s[68:69]
	v_exp_f32_e32 v72, v72
	v_exp_f32_e32 v73, v73
	v_exp_f32_e32 v74, v74
	v_exp_f32_e32 v75, v75
	v_exp_f32_e32 v60, v60
	v_exp_f32_e32 v61, v61
	v_exp_f32_e32 v62, v62
	v_exp_f32_e32 v63, v63
	v_exp_f32_e32 v40, v40
	v_exp_f32_e32 v41, v41
	v_exp_f32_e32 v42, v42
	v_exp_f32_e32 v43, v43
	v_exp_f32_e32 v44, v44
	v_exp_f32_e32 v45, v45
	v_exp_f32_e32 v46, v46
	v_exp_f32_e32 v47, v47
	v_pk_add_f32 v[72:73], v[72:73], s[72:73]
	v_pk_add_f32 v[40:41], v[40:41], s[72:73]
	v_pk_add_f32 v[74:75], v[74:75], s[72:73]
	v_pk_add_f32 v[42:43], v[42:43], s[72:73]
	v_pk_add_f32 v[60:61], v[60:61], s[72:73]
	v_pk_add_f32 v[44:45], v[44:45], s[72:73]
	v_pk_add_f32 v[62:63], v[62:63], s[72:73]
	v_pk_add_f32 v[46:47], v[46:47], s[72:73]
	v_rcp_f32_e32 v72, v72
	v_rcp_f32_e32 v73, v73
	v_rcp_f32_e32 v74, v74
	v_rcp_f32_e32 v75, v75
	v_rcp_f32_e32 v60, v60
	v_rcp_f32_e32 v61, v61
	v_rcp_f32_e32 v62, v62
	v_rcp_f32_e32 v63, v63
	v_rcp_f32_e32 v40, v40
	v_rcp_f32_e32 v41, v41
	v_rcp_f32_e32 v42, v42
	v_rcp_f32_e32 v43, v43
	v_rcp_f32_e32 v44, v44
	v_rcp_f32_e32 v45, v45
	v_rcp_f32_e32 v46, v46
	v_rcp_f32_e32 v47, v47
	s_waitcnt vmcnt(12)
	v_lshlrev_b32_e32 v230, 16, v96
	v_and_b32_e32 v231, 0xffff0000, v96
	v_lshlrev_b32_e32 v234, 16, v97
	v_and_b32_e32 v235, 0xffff0000, v97
	v_lshlrev_b32_e32 v236, 16, v98
	v_and_b32_e32 v237, 0xffff0000, v98
	v_lshlrev_b32_e32 v238, 16, v99
	v_and_b32_e32 v239, 0xffff0000, v99
	v_pk_mul_f32 v[72:73], v[64:65], v[72:73]
	v_pk_mul_f32 v[74:75], v[66:67], v[74:75]
	v_pk_mul_f32 v[60:61], v[52:53], v[60:61]
	v_pk_mul_f32 v[62:63], v[54:55], v[62:63]
	v_pk_mul_f32 v[40:41], v[40:41], v[230:231]
	v_pk_mul_f32 v[42:43], v[42:43], v[234:235]
	v_pk_mul_f32 v[44:45], v[44:45], v[236:237]
	v_pk_mul_f32 v[46:47], v[46:47], v[238:239]
	v_pk_add_f32 v[198:199], v[72:73], v[72:73]
	v_pk_add_f32 v[200:201], v[74:75], v[74:75]
	v_pk_mul_f32 v[206:207], v[198:199], s[70:71]
	v_pk_mul_f32 v[208:209], v[200:201], s[70:71]
	v_pk_fma_f32 v[202:203], v[198:199], s[74:75], v[222:223]
	v_pk_fma_f32 v[204:205], v[200:201], s[74:75], v[222:223]
	v_exp_f32_e32 v206, v206
	v_exp_f32_e32 v207, v207
	v_exp_f32_e32 v208, v208
	v_exp_f32_e32 v209, v209
	v_pk_fma_f32 v[202:203], v[198:199], v[202:203], s[76:77]
	v_pk_fma_f32 v[204:205], v[200:201], v[204:205], s[76:77]
	v_pk_fma_f32 v[202:203], v[198:199], v[202:203], s[72:73]
	v_pk_fma_f32 v[204:205], v[200:201], v[204:205], s[72:73]
	v_pk_mul_f32 v[202:203], v[202:203], v[198:199] neg_lo:[0,1] neg_hi:[0,1]
	v_pk_mul_f32 v[204:205], v[204:205], v[200:201] neg_lo:[0,1] neg_hi:[0,1]
; __device__ __forceinline__ unsigned pk2(float lo, float hi) { unsigned r; asm("v_cvt_pk_bf16_f32 %0, %1, %2" : "=v"(r) : "v"(lo), "v"(hi)); return r; }
; __device__ __forceinline__ float sigmoidf_(float x) { return __builtin_amdgcn_rcpf(1.0f + __expf(-x)); }
;     __device__ __forceinline__ void operator()(const f32x4 (&acc)[2][2][4][2], const Unit& u, int wr, int wc, int fr, int fq) const {
;     ...
;         for (int ai = 0; ai < 2; ++ai)
; #pragma unroll
;             for (int m = 0; m < 4; ++m) { const size_t off = (size_t)(row0 + ai * HALF + m * 16) * LW + ch0;
;                 float xc[8]; unpack8(xraw[ai][m], xc);
;                 float la[8], uu[8];
; #pragma unroll
;                 for (int n = 0; n < 2; ++n)
; #pragma unroll
;                     for (int j = 0; j < 4; ++j) { const int e = 4 * n + j;
;                         const float r = sigmoidf_(acc[ai][0][m][n][j] + br[e]), ig = sigmoidf_(acc[ai][1][m][n][j] + bi[e]);
;                         const float l = -8.0f * r * sp[e]; la[e] = l;
;                         const float x2 = 2.0f * l;
;                         const float om = x2 > -0.03125f ? -x2 * (1.0f + x2 * (0.5f + x2 * (0.16666667f + x2 * 0.041666668f))) : 1.0f - __expf(x2);
;                         uu[e] = __builtin_amdgcn_sqrtf(om) * (ig * xc[e]); }
;                 u32x4 w0, w1; w0.x = pk2(la[0], uu[0]); w0.y = pk2(la[1], uu[1]); w0.z = pk2(la[2], uu[2]); w0.w = pk2(la[3], uu[3]);
;                 w1.x = pk2(la[4], uu[4]); w1.y = pk2(la[5], uu[5]); w1.z = pk2(la[6], uu[6]); w1.w = pk2(la[7], uu[7]);
;                 *(u32x4*)(LU + off) = w0; *(u32x4*)(LU + off + 4) = w1; }
	v_pk_add_f32 v[206:207], s[72:73], v[206:207] neg_lo:[0,1] neg_hi:[0,1]
	v_pk_add_f32 v[208:209], s[72:73], v[208:209] neg_lo:[0,1] neg_hi:[0,1]
	v_cmp_lt_f32_e64 s[78:79], s4, v198
	v_cmp_lt_f32_e64 s[80:81], s4, v199
	v_cmp_lt_f32_e64 s[82:83], s4, v200
	v_cmp_lt_f32_e64 s[24:25], s4, v201
	v_cndmask_b32_e64 v202, v206, v202, s[78:79]
	v_cndmask_b32_e64 v203, v207, v203, s[80:81]
	v_cndmask_b32_e64 v204, v208, v204, s[82:83]
	v_cndmask_b32_e64 v205, v209, v205, s[24:25]
	v_sqrt_f32_e32 v202, v202
	v_sqrt_f32_e32 v203, v203
	v_sqrt_f32_e32 v204, v204
	v_sqrt_f32_e32 v205, v205
	v_pk_mul_f32 v[40:41], v[40:41], v[202:203]
	v_pk_mul_f32 v[42:43], v[42:43], v[204:205]
	v_pk_add_f32 v[198:199], v[60:61], v[60:61]
	v_pk_add_f32 v[200:201], v[62:63], v[62:63]
	v_pk_mul_f32 v[206:207], v[198:199], s[70:71]
	v_pk_mul_f32 v[208:209], v[200:201], s[70:71]
	v_pk_fma_f32 v[202:203], v[198:199], s[74:75], v[222:223]
	v_pk_fma_f32 v[204:205], v[200:201], s[74:75], v[222:223]
	v_exp_f32_e32 v206, v206
	v_exp_f32_e32 v207, v207
	v_exp_f32_e32 v208, v208
	v_exp_f32_e32 v209, v209
	v_pk_fma_f32 v[202:203], v[198:199], v[202:203], s[76:77]
	v_pk_fma_f32 v[204:205], v[200:201], v[204:205], s[76:77]
	v_pk_fma_f32 v[202:203], v[198:199], v[202:203], s[72:73]
	v_pk_fma_f32 v[204:205], v[200:201], v[204:205], s[72:73]
	v_pk_mul_f32 v[202:203], v[202:203], v[198:199] neg_lo:[0,1] neg_hi:[0,1]
	v_pk_mul_f32 v[204:205], v[204:205], v[200:201] neg_lo:[0,1] neg_hi:[0,1]
	v_pk_add_f32 v[206:207], s[72:73], v[206:207] neg_lo:[0,1] neg_hi:[0,1]
	v_pk_add_f32 v[208:209], s[72:73], v[208:209] neg_lo:[0,1] neg_hi:[0,1]
	v_cmp_lt_f32_e64 s[78:79], s4, v198
	v_cmp_lt_f32_e64 s[80:81], s4, v199
	v_cmp_lt_f32_e64 s[82:83], s4, v200
	v_cmp_lt_f32_e64 s[24:25], s4, v201
	v_cndmask_b32_e64 v202, v206, v202, s[78:79]
	v_cndmask_b32_e64 v203, v207, v203, s[80:81]
	v_cndmask_b32_e64 v204, v208, v204, s[82:83]
	v_cndmask_b32_e64 v205, v209, v205, s[24:25]
	v_sqrt_f32_e32 v202, v202
	v_sqrt_f32_e32 v203, v203
	v_sqrt_f32_e32 v204, v204
	v_sqrt_f32_e32 v205, v205
	v_pk_mul_f32 v[44:45], v[44:45], v[202:203]
	v_pk_mul_f32 v[46:47], v[46:47], v[204:205]
	v_cvt_pk_bf16_f32 v40, v72, v40
	v_cvt_pk_bf16_f32 v41, v73, v41
	v_cvt_pk_bf16_f32 v42, v74, v42
	v_cvt_pk_bf16_f32 v43, v75, v43
	v_cvt_pk_bf16_f32 v44, v60, v44
	v_cvt_pk_bf16_f32 v45, v61, v45
	v_cvt_pk_bf16_f32 v46, v62, v46
	v_cvt_pk_bf16_f32 v47, v63, v47
	v_add_u32_e32 v197, 0x120000, v225
	global_store_dwordx4 v197, v[40:43], s[44:45]
	global_store_dwordx4 v197, v[44:47], s[44:45] offset:16
	v_pk_add_f32 v[28:29], v[28:29], v[68:69]
	v_pk_add_f32 v[16:17], v[16:17], v[32:33]
	v_pk_add_f32 v[30:31], v[30:31], v[70:71]
	v_pk_add_f32 v[18:19], v[18:19], v[34:35]
	v_pk_add_f32 v[24:25], v[24:25], v[56:57]
	v_pk_add_f32 v[20:21], v[20:21], v[36:37]
	v_pk_add_f32 v[26:27], v[26:27], v[58:59]
	v_pk_add_f32 v[22:23], v[22:23], v[38:39]
	v_pk_mul_f32 v[28:29], v[28:29], s[68:69]
	v_pk_mul_f32 v[16:17], v[16:17], s[68:69]
	v_pk_mul_f32 v[30:31], v[30:31], s[68:69]
	v_pk_mul_f32 v[18:19], v[18:19], s[68:69]
	v_pk_mul_f32 v[24:25], v[24:25], s[68:69]
	v_pk_mul_f32 v[20:21], v[20:21], s[68:69]
	v_pk_mul_f32 v[26:27], v[26:27], s[68:69]
	v_pk_mul_f32 v[22:23], v[22:23], s[68:69]
	v_exp_f32_e32 v28, v28
	v_exp_f32_e32 v29, v29
	v_exp_f32_e32 v30, v30
	v_exp_f32_e32 v31, v31
	v_exp_f32_e32 v24, v24
	v_exp_f32_e32 v25, v25
	v_exp_f32_e32 v26, v26
	v_exp_f32_e32 v27, v27
	v_exp_f32_e32 v16, v16
	v_exp_f32_e32 v17, v17
	v_exp_f32_e32 v18, v18
	v_exp_f32_e32 v19, v19
	v_exp_f32_e32 v20, v20
	v_exp_f32_e32 v21, v21
	v_exp_f32_e32 v22, v22
	v_exp_f32_e32 v23, v23
	v_pk_add_f32 v[28:29], v[28:29], s[72:73]
	v_pk_add_f32 v[16:17], v[16:17], s[72:73]
	v_pk_add_f32 v[30:31], v[30:31], s[72:73]
	v_pk_add_f32 v[18:19], v[18:19], s[72:73]
	v_pk_add_f32 v[24:25], v[24:25], s[72:73]
	v_pk_add_f32 v[20:21], v[20:21], s[72:73]
	v_pk_add_f32 v[26:27], v[26:27], s[72:73]
	v_pk_add_f32 v[22:23], v[22:23], s[72:73]
	v_rcp_f32_e32 v28, v28
	v_rcp_f32_e32 v29, v29
	v_rcp_f32_e32 v30, v30
	v_rcp_f32_e32 v31, v31
	v_rcp_f32_e32 v24, v24
	v_rcp_f32_e32 v25, v25
	v_rcp_f32_e32 v26, v26
	v_rcp_f32_e32 v27, v27
	v_rcp_f32_e32 v16, v16
	v_rcp_f32_e32 v17, v17
	v_rcp_f32_e32 v18, v18
	v_rcp_f32_e32 v19, v19
	v_rcp_f32_e32 v20, v20
	v_rcp_f32_e32 v21, v21
	v_rcp_f32_e32 v22, v22
	v_rcp_f32_e32 v23, v23
	s_waitcnt vmcnt(13)
; __device__ __forceinline__ unsigned pk2(float lo, float hi) { unsigned r; asm("v_cvt_pk_bf16_f32 %0, %1, %2" : "=v"(r) : "v"(lo), "v"(hi)); return r; }
; __device__ __forceinline__ float sigmoidf_(float x) { return __builtin_amdgcn_rcpf(1.0f + __expf(-x)); }
;     __device__ __forceinline__ void operator()(const f32x4 (&acc)[2][2][4][2], const Unit& u, int wr, int wc, int fr, int fq) const {
;     ...
;         for (int ai = 0; ai < 2; ++ai)
; #pragma unroll
;             for (int m = 0; m < 4; ++m) { const size_t off = (size_t)(row0 + ai * HALF + m * 16) * LW + ch0;
;                 float xc[8]; unpack8(xraw[ai][m], xc);
;                 float la[8], uu[8];
; #pragma unroll
;                 for (int n = 0; n < 2; ++n)
; #pragma unroll
;                     for (int j = 0; j < 4; ++j) { const int e = 4 * n + j;
;                         const float r = sigmoidf_(acc[ai][0][m][n][j] + br[e]), ig = sigmoidf_(acc[ai][1][m][n][j] + bi[e]);
;                         const float l = -8.0f * r * sp[e]; la[e] = l;
;                         const float x2 = 2.0f * l;
;                         const float om = x2 > -0.03125f ? -x2 * (1.0f + x2 * (0.5f + x2 * (0.16666667f + x2 * 0.041666668f))) : 1.0f - __expf(x2);
;                         uu[e] = __builtin_amdgcn_sqrtf(om) * (ig * xc[e]); }
;                 u32x4 w0, w1; w0.x = pk2(la[0], uu[0]); w0.y = pk2(la[1], uu[1]); w0.z = pk2(la[2], uu[2]); w0.w = pk2(la[3], uu[3]);
;                 w1.x = pk2(la[4], uu[4]); w1.y = pk2(la[5], uu[5]); w1.z = pk2(la[6], uu[6]); w1.w = pk2(la[7], uu[7]);
;                 *(u32x4*)(LU + off) = w0; *(u32x4*)(LU + off + 4) = w1; }
	v_lshlrev_b32_e32 v230, 16, v76
	v_and_b32_e32 v231, 0xffff0000, v76
	v_lshlrev_b32_e32 v234, 16, v77
	v_and_b32_e32 v235, 0xffff0000, v77
	v_lshlrev_b32_e32 v236, 16, v78
	v_and_b32_e32 v237, 0xffff0000, v78
	v_lshlrev_b32_e32 v238, 16, v79
	v_and_b32_e32 v239, 0xffff0000, v79
	v_pk_mul_f32 v[28:29], v[64:65], v[28:29]
	v_pk_mul_f32 v[30:31], v[66:67], v[30:31]
	v_pk_mul_f32 v[24:25], v[52:53], v[24:25]
	v_pk_mul_f32 v[26:27], v[54:55], v[26:27]
	v_pk_mul_f32 v[16:17], v[16:17], v[230:231]
	v_pk_mul_f32 v[18:19], v[18:19], v[234:235]
	v_pk_mul_f32 v[20:21], v[20:21], v[236:237]
	v_pk_mul_f32 v[22:23], v[22:23], v[238:239]
	v_pk_add_f32 v[198:199], v[28:29], v[28:29]
	v_pk_add_f32 v[200:201], v[30:31], v[30:31]
	v_pk_mul_f32 v[206:207], v[198:199], s[70:71]
	v_pk_mul_f32 v[208:209], v[200:201], s[70:71]
	v_pk_fma_f32 v[202:203], v[198:199], s[74:75], v[222:223]
	v_pk_fma_f32 v[204:205], v[200:201], s[74:75], v[222:223]
	v_exp_f32_e32 v206, v206
	v_exp_f32_e32 v207, v207
	v_exp_f32_e32 v208, v208
	v_exp_f32_e32 v209, v209
	v_pk_fma_f32 v[202:203], v[198:199], v[202:203], s[76:77]
	v_pk_fma_f32 v[204:205], v[200:201], v[204:205], s[76:77]
	v_pk_fma_f32 v[202:203], v[198:199], v[202:203], s[72:73]
	v_pk_fma_f32 v[204:205], v[200:201], v[204:205], s[72:73]
	v_pk_mul_f32 v[202:203], v[202:203], v[198:199] neg_lo:[0,1] neg_hi:[0,1]
	v_pk_mul_f32 v[204:205], v[204:205], v[200:201] neg_lo:[0,1] neg_hi:[0,1]
	v_pk_add_f32 v[206:207], s[72:73], v[206:207] neg_lo:[0,1] neg_hi:[0,1]
	v_pk_add_f32 v[208:209], s[72:73], v[208:209] neg_lo:[0,1] neg_hi:[0,1]
	v_cmp_lt_f32_e64 s[78:79], s4, v198
	v_cmp_lt_f32_e64 s[80:81], s4, v199
	v_cmp_lt_f32_e64 s[82:83], s4, v200
	v_cmp_lt_f32_e64 s[24:25], s4, v201
	v_cndmask_b32_e64 v202, v206, v202, s[78:79]
	v_cndmask_b32_e64 v203, v207, v203, s[80:81]
	v_cndmask_b32_e64 v204, v208, v204, s[82:83]
	v_cndmask_b32_e64 v205, v209, v205, s[24:25]
	v_sqrt_f32_e32 v202, v202
	v_sqrt_f32_e32 v203, v203
	v_sqrt_f32_e32 v204, v204
	v_sqrt_f32_e32 v205, v205
	v_pk_mul_f32 v[16:17], v[16:17], v[202:203]
	v_pk_mul_f32 v[18:19], v[18:19], v[204:205]
	v_pk_add_f32 v[198:199], v[24:25], v[24:25]
	v_pk_add_f32 v[200:201], v[26:27], v[26:27]
	v_pk_mul_f32 v[206:207], v[198:199], s[70:71]
	v_pk_mul_f32 v[208:209], v[200:201], s[70:71]
	v_pk_fma_f32 v[202:203], v[198:199], s[74:75], v[222:223]
	v_pk_fma_f32 v[204:205], v[200:201], s[74:75], v[222:223]
	v_exp_f32_e32 v206, v206
	v_exp_f32_e32 v207, v207
	v_exp_f32_e32 v208, v208
	v_exp_f32_e32 v209, v209
	v_pk_fma_f32 v[202:203], v[198:199], v[202:203], s[76:77]
	v_pk_fma_f32 v[204:205], v[200:201], v[204:205], s[76:77]
	v_pk_fma_f32 v[202:203], v[198:199], v[202:203], s[72:73]
	v_pk_fma_f32 v[204:205], v[200:201], v[204:205], s[72:73]
	v_pk_mul_f32 v[202:203], v[202:203], v[198:199] neg_lo:[0,1] neg_hi:[0,1]
	v_pk_mul_f32 v[204:205], v[204:205], v[200:201] neg_lo:[0,1] neg_hi:[0,1]
	v_pk_add_f32 v[206:207], s[72:73], v[206:207] neg_lo:[0,1] neg_hi:[0,1]
	v_pk_add_f32 v[208:209], s[72:73], v[208:209] neg_lo:[0,1] neg_hi:[0,1]
	v_cmp_lt_f32_e64 s[78:79], s4, v198
	v_cmp_lt_f32_e64 s[80:81], s4, v199
	v_cmp_lt_f32_e64 s[82:83], s4, v200
	v_cmp_lt_f32_e64 s[24:25], s4, v201
	v_cndmask_b32_e64 v202, v206, v202, s[78:79]
	v_cndmask_b32_e64 v203, v207, v203, s[80:81]
	v_cndmask_b32_e64 v204, v208, v204, s[82:83]
	v_cndmask_b32_e64 v205, v209, v205, s[24:25]
	v_sqrt_f32_e32 v202, v202
	v_sqrt_f32_e32 v203, v203
	v_sqrt_f32_e32 v204, v204
	v_sqrt_f32_e32 v205, v205
	v_pk_mul_f32 v[20:21], v[20:21], v[202:203]
	v_pk_mul_f32 v[22:23], v[22:23], v[204:205]
	v_cvt_pk_bf16_f32 v16, v28, v16
	v_cvt_pk_bf16_f32 v17, v29, v17
	v_cvt_pk_bf16_f32 v18, v30, v18
	v_cvt_pk_bf16_f32 v19, v31, v19
	v_cvt_pk_bf16_f32 v20, v24, v20
	v_cvt_pk_bf16_f32 v21, v25, v21
	v_cvt_pk_bf16_f32 v22, v26, v22
	v_cvt_pk_bf16_f32 v23, v27, v23
	v_add_u32_e32 v197, 0x140000, v225
	global_store_dwordx4 v197, v[16:19], s[44:45]
	global_store_dwordx4 v197, v[20:23], s[44:45] offset:16
	v_pk_add_f32 v[12:13], v[12:13], v[68:69]
	v_pk_add_f32 v[0:1], v[0:1], v[32:33]
	v_pk_add_f32 v[14:15], v[14:15], v[70:71]
	v_pk_add_f32 v[2:3], v[2:3], v[34:35]
	v_pk_add_f32 v[8:9], v[8:9], v[56:57]
	v_pk_add_f32 v[4:5], v[4:5], v[36:37]
	v_pk_add_f32 v[10:11], v[10:11], v[58:59]
	v_pk_add_f32 v[6:7], v[6:7], v[38:39]
	v_pk_mul_f32 v[12:13], v[12:13], s[68:69]
	v_pk_mul_f32 v[0:1], v[0:1], s[68:69]
	v_pk_mul_f32 v[14:15], v[14:15], s[68:69]
	v_pk_mul_f32 v[2:3], v[2:3], s[68:69]
	v_pk_mul_f32 v[8:9], v[8:9], s[68:69]
	v_pk_mul_f32 v[4:5], v[4:5], s[68:69]
	v_pk_mul_f32 v[10:11], v[10:11], s[68:69]
	v_pk_mul_f32 v[6:7], v[6:7], s[68:69]
	v_exp_f32_e32 v12, v12
	v_exp_f32_e32 v13, v13
	v_exp_f32_e32 v14, v14
	v_exp_f32_e32 v15, v15
	v_exp_f32_e32 v8, v8
	v_exp_f32_e32 v9, v9
	v_exp_f32_e32 v10, v10
	v_exp_f32_e32 v11, v11
	v_exp_f32_e32 v0, v0
	v_exp_f32_e32 v1, v1
	v_exp_f32_e32 v2, v2
	v_exp_f32_e32 v3, v3
	v_exp_f32_e32 v4, v4
	v_exp_f32_e32 v5, v5
	v_exp_f32_e32 v6, v6
	v_exp_f32_e32 v7, v7
	v_pk_add_f32 v[12:13], v[12:13], s[72:73]
	v_pk_add_f32 v[0:1], v[0:1], s[72:73]
	v_pk_add_f32 v[14:15], v[14:15], s[72:73]
	v_pk_add_f32 v[2:3], v[2:3], s[72:73]
	v_pk_add_f32 v[8:9], v[8:9], s[72:73]
	v_pk_add_f32 v[4:5], v[4:5], s[72:73]
	v_pk_add_f32 v[10:11], v[10:11], s[72:73]
	v_pk_add_f32 v[6:7], v[6:7], s[72:73]
	v_rcp_f32_e32 v12, v12
	v_rcp_f32_e32 v13, v13
	v_rcp_f32_e32 v14, v14
	v_rcp_f32_e32 v15, v15
	v_rcp_f32_e32 v8, v8
	v_rcp_f32_e32 v9, v9
	v_rcp_f32_e32 v10, v10
	v_rcp_f32_e32 v11, v11
	v_rcp_f32_e32 v0, v0
	v_rcp_f32_e32 v1, v1
	v_rcp_f32_e32 v2, v2
	v_rcp_f32_e32 v3, v3
	v_rcp_f32_e32 v4, v4
	v_rcp_f32_e32 v5, v5
	v_rcp_f32_e32 v6, v6
	v_rcp_f32_e32 v7, v7
	s_waitcnt vmcnt(14)
; __device__ __forceinline__ unsigned pk2(float lo, float hi) { unsigned r; asm("v_cvt_pk_bf16_f32 %0, %1, %2" : "=v"(r) : "v"(lo), "v"(hi)); return r; }
; __device__ __forceinline__ float sigmoidf_(float x) { return __builtin_amdgcn_rcpf(1.0f + __expf(-x)); }
; template <class Epi, class S_t>
; __device__ __forceinline__ void gemm_phase(LAS unsigned char* lds, int lda, int ldb, const S_t& S, const Epi& E) {
;     ...
;         if (!has_next) break;
; #pragma unroll
;         for (int a = 0; a < 2; ++a)
; #pragma unroll
;             for (int b = 0; b < 2; ++b)
; #pragma unroll
;                 for (int m = 0; m < 4; ++m)
; #pragma unroll
;                     for (int n = 0; n < 2; ++n) acc[a][b][m][n] = (f32x4){0.f, 0.f, 0.f, 0.f};
;         cur = nxt; cA = nA; cB = nB; ++ui;
;     __device__ __forceinline__ void operator()(const f32x4 (&acc)[2][2][4][2], const Unit& u, int wr, int wc, int fr, int fq) const {
;     ...
;                         const float r = sigmoidf_(acc[ai][0][m][n][j] + br[e]), ig = sigmoidf_(acc[ai][1][m][n][j] + bi[e]);
;                         const float l = -8.0f * r * sp[e]; la[e] = l;
;                         const float x2 = 2.0f * l;
;                         const float om = x2 > -0.03125f ? -x2 * (1.0f + x2 * (0.5f + x2 * (0.16666667f + x2 * 0.041666668f))) : 1.0f - __expf(x2);
;                         uu[e] = __builtin_amdgcn_sqrtf(om) * (ig * xc[e]); }
;                 u32x4 w0, w1; w0.x = pk2(la[0], uu[0]); w0.y = pk2(la[1], uu[1]); w0.z = pk2(la[2], uu[2]); w0.w = pk2(la[3], uu[3]);
;                 w1.x = pk2(la[4], uu[4]); w1.y = pk2(la[5], uu[5]); w1.z = pk2(la[6], uu[6]); w1.w = pk2(la[7], uu[7]);
;                 *(u32x4*)(LU + off) = w0; *(u32x4*)(LU + off + 4) = w1; }
	v_lshlrev_b32_e32 v230, 16, v48
	v_and_b32_e32 v231, 0xffff0000, v48
	v_lshlrev_b32_e32 v234, 16, v49
	v_and_b32_e32 v235, 0xffff0000, v49
	v_lshlrev_b32_e32 v236, 16, v50
	v_and_b32_e32 v237, 0xffff0000, v50
	v_lshlrev_b32_e32 v238, 16, v51
	v_and_b32_e32 v239, 0xffff0000, v51
	v_pk_mul_f32 v[12:13], v[64:65], v[12:13]
	v_pk_mul_f32 v[14:15], v[66:67], v[14:15]
	v_pk_mul_f32 v[8:9], v[52:53], v[8:9]
	v_pk_mul_f32 v[10:11], v[54:55], v[10:11]
	v_pk_mul_f32 v[0:1], v[0:1], v[230:231]
	v_pk_mul_f32 v[2:3], v[2:3], v[234:235]
	v_pk_mul_f32 v[4:5], v[4:5], v[236:237]
	v_pk_mul_f32 v[6:7], v[6:7], v[238:239]
	v_pk_add_f32 v[198:199], v[12:13], v[12:13]
	v_pk_add_f32 v[200:201], v[14:15], v[14:15]
	v_pk_mul_f32 v[206:207], v[198:199], s[70:71]
	v_pk_mul_f32 v[208:209], v[200:201], s[70:71]
	v_pk_fma_f32 v[202:203], v[198:199], s[74:75], v[222:223]
	v_pk_fma_f32 v[204:205], v[200:201], s[74:75], v[222:223]
	v_exp_f32_e32 v206, v206
	v_exp_f32_e32 v207, v207
	v_exp_f32_e32 v208, v208
	v_exp_f32_e32 v209, v209
	v_pk_fma_f32 v[202:203], v[198:199], v[202:203], s[76:77]
	v_pk_fma_f32 v[204:205], v[200:201], v[204:205], s[76:77]
	v_pk_fma_f32 v[202:203], v[198:199], v[202:203], s[72:73]
	v_pk_fma_f32 v[204:205], v[200:201], v[204:205], s[72:73]
	v_pk_mul_f32 v[202:203], v[202:203], v[198:199] neg_lo:[0,1] neg_hi:[0,1]
	v_pk_mul_f32 v[204:205], v[204:205], v[200:201] neg_lo:[0,1] neg_hi:[0,1]
	v_pk_add_f32 v[206:207], s[72:73], v[206:207] neg_lo:[0,1] neg_hi:[0,1]
	v_pk_add_f32 v[208:209], s[72:73], v[208:209] neg_lo:[0,1] neg_hi:[0,1]
	v_cmp_lt_f32_e64 s[78:79], s4, v198
	v_cmp_lt_f32_e64 s[80:81], s4, v199
	v_cmp_lt_f32_e64 s[82:83], s4, v200
	v_cmp_lt_f32_e64 s[24:25], s4, v201
	v_cndmask_b32_e64 v202, v206, v202, s[78:79]
	v_cndmask_b32_e64 v203, v207, v203, s[80:81]
	v_cndmask_b32_e64 v204, v208, v204, s[82:83]
	v_cndmask_b32_e64 v205, v209, v205, s[24:25]
	v_sqrt_f32_e32 v202, v202
	v_sqrt_f32_e32 v203, v203
	v_sqrt_f32_e32 v204, v204
	v_sqrt_f32_e32 v205, v205
	v_pk_mul_f32 v[0:1], v[0:1], v[202:203]
	v_pk_mul_f32 v[2:3], v[2:3], v[204:205]
	v_pk_add_f32 v[198:199], v[8:9], v[8:9]
	v_pk_add_f32 v[200:201], v[10:11], v[10:11]
	v_pk_mul_f32 v[206:207], v[198:199], s[70:71]
	v_pk_mul_f32 v[208:209], v[200:201], s[70:71]
	v_pk_fma_f32 v[202:203], v[198:199], s[74:75], v[222:223]
	v_pk_fma_f32 v[204:205], v[200:201], s[74:75], v[222:223]
	v_exp_f32_e32 v206, v206
	v_exp_f32_e32 v207, v207
	v_exp_f32_e32 v208, v208
	v_exp_f32_e32 v209, v209
	v_pk_fma_f32 v[202:203], v[198:199], v[202:203], s[76:77]
	v_pk_fma_f32 v[204:205], v[200:201], v[204:205], s[76:77]
	v_pk_fma_f32 v[202:203], v[198:199], v[202:203], s[72:73]
	v_pk_fma_f32 v[204:205], v[200:201], v[204:205], s[72:73]
	v_pk_mul_f32 v[202:203], v[202:203], v[198:199] neg_lo:[0,1] neg_hi:[0,1]
	v_pk_mul_f32 v[204:205], v[204:205], v[200:201] neg_lo:[0,1] neg_hi:[0,1]
	v_pk_add_f32 v[206:207], s[72:73], v[206:207] neg_lo:[0,1] neg_hi:[0,1]
	v_pk_add_f32 v[208:209], s[72:73], v[208:209] neg_lo:[0,1] neg_hi:[0,1]
	v_cmp_lt_f32_e64 s[78:79], s4, v198
	v_cmp_lt_f32_e64 s[80:81], s4, v199
	v_cmp_lt_f32_e64 s[82:83], s4, v200
	v_cmp_lt_f32_e64 s[24:25], s4, v201
	v_cndmask_b32_e64 v202, v206, v202, s[78:79]
	v_cndmask_b32_e64 v203, v207, v203, s[80:81]
	v_cndmask_b32_e64 v204, v208, v204, s[82:83]
	v_cndmask_b32_e64 v205, v209, v205, s[24:25]
	v_sqrt_f32_e32 v202, v202
	v_sqrt_f32_e32 v203, v203
	v_sqrt_f32_e32 v204, v204
	v_sqrt_f32_e32 v205, v205
	v_pk_mul_f32 v[4:5], v[4:5], v[202:203]
	v_pk_mul_f32 v[6:7], v[6:7], v[204:205]
	v_cvt_pk_bf16_f32 v0, v12, v0
	v_cvt_pk_bf16_f32 v1, v13, v1
	v_cvt_pk_bf16_f32 v2, v14, v2
	v_cvt_pk_bf16_f32 v3, v15, v3
	v_cvt_pk_bf16_f32 v4, v8, v4
	v_cvt_pk_bf16_f32 v5, v9, v5
	v_cvt_pk_bf16_f32 v6, v10, v6
	v_cvt_pk_bf16_f32 v7, v11, v7
	s_and_b64 vcc, exec, s[6:7]
	s_mov_b32 s42, s14
	s_mov_b32 s5, s18
	s_mov_b64 s[62:63], s[58:59]
	s_mov_b64 s[60:61], s[56:57]
	v_add_u32_e32 v197, 0x160000, v225
	global_store_dwordx4 v197, v[0:3], s[44:45]
	global_store_dwordx4 v197, v[4:7], s[44:45] offset:16
	s_cbranch_vccnz .LBB0_804
	s_branch .LBB0_544

; template <class Epi, class S_t>
; __device__ __forceinline__ void gemm_phase(LAS unsigned char* lds, int lda, int ldb, const S_t& S, const Epi& E) {
;     ...
; #pragma unroll
;         for (int a = 0; a < 2; ++a)
; #pragma unroll
;             for (int b = 0; b < 2; ++b)
; #pragma unroll
;                 for (int m = 0; m < 4; ++m)
; #pragma unroll
;                     for (int n = 0; n < 2; ++n) acc[a][b][m][n] = (f32x4){0.f, 0.f, 0.f, 0.f};
;         cur = nxt; cA = nA; cB = nB; ++ui;
.LBB0_944:
	s_add_u32 s60, s60, 0x40080
	s_addc_u32 s61, s61, 0
	s_add_u32 s0, s62, 0x100
	s_addc_u32 s1, s63, 0
	s_mov_b32 s43, -2
	v_mov_b64_e32 v[0:1], 0
	v_mov_b64_e32 v[2:3], 0
	v_mov_b64_e32 v[4:5], 0
	v_mov_b64_e32 v[6:7], 0
	v_mov_b64_e32 v[8:9], 0
	v_mov_b64_e32 v[10:11], 0
	v_mov_b64_e32 v[12:13], 0
	v_mov_b64_e32 v[14:15], 0
	v_mov_b64_e32 v[16:17], 0
	v_mov_b64_e32 v[18:19], 0
	v_mov_b64_e32 v[20:21], 0
	v_mov_b64_e32 v[22:23], 0
	v_mov_b64_e32 v[24:25], 0
	v_mov_b64_e32 v[26:27], 0
	v_mov_b64_e32 v[28:29], 0
	v_mov_b64_e32 v[30:31], 0
	v_mov_b64_e32 v[32:33], 0
	v_mov_b64_e32 v[34:35], 0
	v_mov_b64_e32 v[36:37], 0
	v_mov_b64_e32 v[38:39], 0
	v_mov_b64_e32 v[40:41], 0
	v_mov_b64_e32 v[42:43], 0
	v_mov_b64_e32 v[44:45], 0
	v_mov_b64_e32 v[46:47], 0
	v_mov_b64_e32 v[48:49], 0
	v_mov_b64_e32 v[50:51], 0
	v_mov_b64_e32 v[52:53], 0
	v_mov_b64_e32 v[54:55], 0
	v_mov_b64_e32 v[56:57], 0
	v_mov_b64_e32 v[58:59], 0
	v_mov_b64_e32 v[60:61], 0
	v_mov_b64_e32 v[62:63], 0
	v_mov_b64_e32 v[64:65], 0
	v_mov_b64_e32 v[66:67], 0
	v_mov_b64_e32 v[68:69], 0
	v_mov_b64_e32 v[70:71], 0
	v_mov_b64_e32 v[72:73], 0
	v_mov_b64_e32 v[74:75], 0
	v_mov_b64_e32 v[76:77], 0
	v_mov_b64_e32 v[78:79], 0
	v_mov_b64_e32 v[80:81], 0
	v_mov_b64_e32 v[82:83], 0
	v_mov_b64_e32 v[84:85], 0
	v_mov_b64_e32 v[86:87], 0
	v_mov_b64_e32 v[88:89], 0
	v_mov_b64_e32 v[90:91], 0
	v_mov_b64_e32 v[92:93], 0
	v_mov_b64_e32 v[94:95], 0
	v_mov_b64_e32 v[96:97], 0
	v_mov_b64_e32 v[98:99], 0
	v_mov_b64_e32 v[100:101], 0
	v_mov_b64_e32 v[102:103], 0
	v_mov_b64_e32 v[104:105], 0
	v_mov_b64_e32 v[106:107], 0
	v_mov_b64_e32 v[108:109], 0
	v_mov_b64_e32 v[110:111], 0
	v_mov_b64_e32 v[112:113], 0
	v_mov_b64_e32 v[114:115], 0
	v_mov_b64_e32 v[116:117], 0
	v_mov_b64_e32 v[118:119], 0
	v_mov_b64_e32 v[120:121], 0
	v_mov_b64_e32 v[122:123], 0
	v_mov_b64_e32 v[124:125], 0
	v_mov_b64_e32 v[126:127], 0

; template <class Epi, class S_t>
; __device__ __forceinline__ void gemm_phase(LAS unsigned char* lds, int lda, int ldb, const S_t& S, const Epi& E) {
;     ...
; #pragma unroll
;         for (int a = 0; a < 2; ++a)
; #pragma unroll
;             for (int b = 0; b < 2; ++b)
; #pragma unroll
;                 for (int m = 0; m < 4; ++m)
; #pragma unroll
;                     for (int n = 0; n < 2; ++n) acc[a][b][m][n] = (f32x4){0.f, 0.f, 0.f, 0.f};
;         cur = nxt; cA = nA; cB = nB; ++ui;
.LBB0_965:
	s_add_u32 s56, s56, 0x80080
	s_addc_u32 s57, s57, 0
	s_add_u32 s0, s58, 0x100
	s_addc_u32 s1, s59, 0
	s_mov_b32 s43, -2
	v_mov_b64_e32 v[0:1], 0
	v_mov_b64_e32 v[2:3], 0
	v_mov_b64_e32 v[4:5], 0
	v_mov_b64_e32 v[6:7], 0
	v_mov_b64_e32 v[8:9], 0
	v_mov_b64_e32 v[10:11], 0
	v_mov_b64_e32 v[12:13], 0
	v_mov_b64_e32 v[14:15], 0
	v_mov_b64_e32 v[16:17], 0
	v_mov_b64_e32 v[18:19], 0
	v_mov_b64_e32 v[20:21], 0
	v_mov_b64_e32 v[22:23], 0
	v_mov_b64_e32 v[24:25], 0
	v_mov_b64_e32 v[26:27], 0
	v_mov_b64_e32 v[28:29], 0
	v_mov_b64_e32 v[30:31], 0
	v_mov_b64_e32 v[32:33], 0
	v_mov_b64_e32 v[34:35], 0
	v_mov_b64_e32 v[36:37], 0
	v_mov_b64_e32 v[38:39], 0
	v_mov_b64_e32 v[40:41], 0
	v_mov_b64_e32 v[42:43], 0
	v_mov_b64_e32 v[44:45], 0
	v_mov_b64_e32 v[46:47], 0
	v_mov_b64_e32 v[48:49], 0
	v_mov_b64_e32 v[50:51], 0
	v_mov_b64_e32 v[52:53], 0
	v_mov_b64_e32 v[54:55], 0
	v_mov_b64_e32 v[56:57], 0
	v_mov_b64_e32 v[58:59], 0
	v_mov_b64_e32 v[60:61], 0
	v_mov_b64_e32 v[62:63], 0
	v_mov_b64_e32 v[64:65], 0
	v_mov_b64_e32 v[66:67], 0
	v_mov_b64_e32 v[68:69], 0
	v_mov_b64_e32 v[70:71], 0
	v_mov_b64_e32 v[72:73], 0
	v_mov_b64_e32 v[74:75], 0
	v_mov_b64_e32 v[76:77], 0
	v_mov_b64_e32 v[78:79], 0
	v_mov_b64_e32 v[80:81], 0
	v_mov_b64_e32 v[82:83], 0
	v_mov_b64_e32 v[84:85], 0
	v_mov_b64_e32 v[86:87], 0
	v_mov_b64_e32 v[88:89], 0
	v_mov_b64_e32 v[90:91], 0
	v_mov_b64_e32 v[92:93], 0
	v_mov_b64_e32 v[94:95], 0
	v_mov_b64_e32 v[96:97], 0
	v_mov_b64_e32 v[98:99], 0
	v_mov_b64_e32 v[100:101], 0
	v_mov_b64_e32 v[102:103], 0
	v_mov_b64_e32 v[104:105], 0
	v_mov_b64_e32 v[106:107], 0
	v_mov_b64_e32 v[108:109], 0
	v_mov_b64_e32 v[110:111], 0
	v_mov_b64_e32 v[112:113], 0
	v_mov_b64_e32 v[114:115], 0
	v_mov_b64_e32 v[116:117], 0
	v_mov_b64_e32 v[118:119], 0
	v_mov_b64_e32 v[120:121], 0
	v_mov_b64_e32 v[122:123], 0
	v_mov_b64_e32 v[124:125], 0
	v_mov_b64_e32 v[126:127], 0

; template <class Epi, class S_t>
; __device__ __forceinline__ void gemm_phase(LAS unsigned char* lds, int lda, int ldb, const S_t& S, const Epi& E) {
;     ...
; #pragma unroll
;         for (int a = 0; a < 2; ++a)
; #pragma unroll
;             for (int b = 0; b < 2; ++b)
; #pragma unroll
;                 for (int m = 0; m < 4; ++m)
; #pragma unroll
;                     for (int n = 0; n < 2; ++n) acc[a][b][m][n] = (f32x4){0.f, 0.f, 0.f, 0.f};
;         cur = nxt; cA = nA; cB = nB; ++ui;
.LBB0_1050:
	s_add_i32 s0, s42, -2
	s_add_u32 s60, s60, 0x80080
	s_addc_u32 s61, s61, 0
	s_add_u32 s1, s62, 0x100
	s_addc_u32 s69, s63, 0
	s_mov_b32 s62, 0
	v_mov_b64_e32 v[0:1], 0
	v_mov_b64_e32 v[2:3], 0
	v_mov_b64_e32 v[4:5], 0
	v_mov_b64_e32 v[6:7], 0
	v_mov_b64_e32 v[8:9], 0
	v_mov_b64_e32 v[10:11], 0
	v_mov_b64_e32 v[12:13], 0
	v_mov_b64_e32 v[14:15], 0
	v_mov_b64_e32 v[16:17], 0
	v_mov_b64_e32 v[18:19], 0
	v_mov_b64_e32 v[20:21], 0
	v_mov_b64_e32 v[22:23], 0
	v_mov_b64_e32 v[24:25], 0
	v_mov_b64_e32 v[26:27], 0
	v_mov_b64_e32 v[28:29], 0
	v_mov_b64_e32 v[30:31], 0
	v_mov_b64_e32 v[32:33], 0
	v_mov_b64_e32 v[34:35], 0
	v_mov_b64_e32 v[36:37], 0
	v_mov_b64_e32 v[38:39], 0
	v_mov_b64_e32 v[40:41], 0
	v_mov_b64_e32 v[42:43], 0
	v_mov_b64_e32 v[44:45], 0
	v_mov_b64_e32 v[46:47], 0
	v_mov_b64_e32 v[48:49], 0
	v_mov_b64_e32 v[50:51], 0
	v_mov_b64_e32 v[52:53], 0
	v_mov_b64_e32 v[54:55], 0
	v_mov_b64_e32 v[56:57], 0
	v_mov_b64_e32 v[58:59], 0
	v_mov_b64_e32 v[60:61], 0
	v_mov_b64_e32 v[62:63], 0
	v_mov_b64_e32 v[64:65], 0
	v_mov_b64_e32 v[66:67], 0
	v_mov_b64_e32 v[68:69], 0
	v_mov_b64_e32 v[70:71], 0
	v_mov_b64_e32 v[72:73], 0
	v_mov_b64_e32 v[74:75], 0
	v_mov_b64_e32 v[76:77], 0
	v_mov_b64_e32 v[78:79], 0
	v_mov_b64_e32 v[80:81], 0
	v_mov_b64_e32 v[82:83], 0
	v_mov_b64_e32 v[84:85], 0
	v_mov_b64_e32 v[86:87], 0
	v_mov_b64_e32 v[88:89], 0
	v_mov_b64_e32 v[90:91], 0
	v_mov_b64_e32 v[92:93], 0
	v_mov_b64_e32 v[94:95], 0
	v_mov_b64_e32 v[96:97], 0
	v_mov_b64_e32 v[98:99], 0
	v_mov_b64_e32 v[100:101], 0
	v_mov_b64_e32 v[102:103], 0
	v_mov_b64_e32 v[104:105], 0
	v_mov_b64_e32 v[106:107], 0
	v_mov_b64_e32 v[108:109], 0
	v_mov_b64_e32 v[110:111], 0
	v_mov_b64_e32 v[112:113], 0
	v_mov_b64_e32 v[114:115], 0
	v_mov_b64_e32 v[116:117], 0
	v_mov_b64_e32 v[118:119], 0
	v_mov_b64_e32 v[120:121], 0
	v_mov_b64_e32 v[122:123], 0
	v_mov_b64_e32 v[124:125], 0
	v_mov_b64_e32 v[126:127], 0

; template <class Epi, class S_t>
; __device__ __forceinline__ void gemm_phase(LAS unsigned char* lds, int lda, int ldb, const S_t& S, const Epi& E) {
;     ...
; #pragma unroll
;         for (int a = 0; a < 2; ++a)
; #pragma unroll
;             for (int b = 0; b < 2; ++b)
; #pragma unroll
;                 for (int m = 0; m < 4; ++m)
; #pragma unroll
;                     for (int n = 0; n < 2; ++n) acc[a][b][m][n] = (f32x4){0.f, 0.f, 0.f, 0.f};
;         cur = nxt; cA = nA; cB = nB; ++ui;
.LBB0_1199:
	s_add_u32 s74, s74, 0x80080
	s_addc_u32 s75, s75, 0
	s_add_u32 s0, s76, 0x100
	s_addc_u32 s1, s77, 0
	s_mov_b32 s5, -2
	v_mov_b64_e32 v[0:1], 0
	v_mov_b64_e32 v[2:3], 0
	v_mov_b64_e32 v[4:5], 0
	v_mov_b64_e32 v[6:7], 0
	v_mov_b64_e32 v[8:9], 0
	v_mov_b64_e32 v[10:11], 0
	v_mov_b64_e32 v[12:13], 0
	v_mov_b64_e32 v[14:15], 0
	v_mov_b64_e32 v[16:17], 0
	v_mov_b64_e32 v[18:19], 0
	v_mov_b64_e32 v[20:21], 0
	v_mov_b64_e32 v[22:23], 0
	v_mov_b64_e32 v[24:25], 0
	v_mov_b64_e32 v[26:27], 0
	v_mov_b64_e32 v[28:29], 0
	v_mov_b64_e32 v[30:31], 0
	v_mov_b64_e32 v[32:33], 0
	v_mov_b64_e32 v[34:35], 0
	v_mov_b64_e32 v[36:37], 0
	v_mov_b64_e32 v[38:39], 0
	v_mov_b64_e32 v[40:41], 0
	v_mov_b64_e32 v[42:43], 0
	v_mov_b64_e32 v[44:45], 0
	v_mov_b64_e32 v[46:47], 0
	v_mov_b64_e32 v[48:49], 0
	v_mov_b64_e32 v[50:51], 0
	v_mov_b64_e32 v[52:53], 0
	v_mov_b64_e32 v[54:55], 0
	v_mov_b64_e32 v[56:57], 0
	v_mov_b64_e32 v[58:59], 0
	v_mov_b64_e32 v[60:61], 0
	v_mov_b64_e32 v[62:63], 0
	v_mov_b64_e32 v[64:65], 0
	v_mov_b64_e32 v[66:67], 0
	v_mov_b64_e32 v[68:69], 0
	v_mov_b64_e32 v[70:71], 0
	v_mov_b64_e32 v[72:73], 0
	v_mov_b64_e32 v[74:75], 0
	v_mov_b64_e32 v[76:77], 0
	v_mov_b64_e32 v[78:79], 0
	v_mov_b64_e32 v[80:81], 0
	v_mov_b64_e32 v[82:83], 0
	v_mov_b64_e32 v[84:85], 0
	v_mov_b64_e32 v[86:87], 0
	v_mov_b64_e32 v[88:89], 0
	v_mov_b64_e32 v[90:91], 0
	v_mov_b64_e32 v[92:93], 0
	v_mov_b64_e32 v[94:95], 0
	v_mov_b64_e32 v[96:97], 0
	v_mov_b64_e32 v[98:99], 0
	v_mov_b64_e32 v[100:101], 0
	v_mov_b64_e32 v[102:103], 0
	v_mov_b64_e32 v[104:105], 0
	v_mov_b64_e32 v[106:107], 0
	v_mov_b64_e32 v[108:109], 0
	v_mov_b64_e32 v[110:111], 0
	v_mov_b64_e32 v[112:113], 0
	v_mov_b64_e32 v[114:115], 0
	v_mov_b64_e32 v[116:117], 0
	v_mov_b64_e32 v[118:119], 0
	v_mov_b64_e32 v[120:121], 0
	v_mov_b64_e32 v[122:123], 0
	v_mov_b64_e32 v[124:125], 0
	v_mov_b64_e32 v[126:127], 0

; template <class Epi, class S_t>
; __device__ __forceinline__ void gemm_phase(LAS unsigned char* lds, int lda, int ldb, const S_t& S, const Epi& E) {
;     ...
; #pragma unroll
;         for (int a = 0; a < 2; ++a)
; #pragma unroll
;             for (int b = 0; b < 2; ++b)
; #pragma unroll
;                 for (int m = 0; m < 4; ++m)
; #pragma unroll
;                     for (int n = 0; n < 2; ++n) acc[a][b][m][n] = (f32x4){0.f, 0.f, 0.f, 0.f};
;         cur = nxt; cA = nA; cB = nB; ++ui;
.LBB0_1382:
	s_add_i32 s0, s69, -2
	s_add_u32 s1, s48, 0x100
	s_addc_u32 s70, s49, 0
	s_mov_b32 s50, 0
	v_mov_b64_e32 v[0:1], 0
	v_mov_b64_e32 v[2:3], 0
	v_mov_b64_e32 v[4:5], 0
	v_mov_b64_e32 v[6:7], 0
	v_mov_b64_e32 v[8:9], 0
	v_mov_b64_e32 v[10:11], 0
	v_mov_b64_e32 v[12:13], 0
	v_mov_b64_e32 v[14:15], 0
	v_mov_b64_e32 v[16:17], 0
	v_mov_b64_e32 v[18:19], 0
	v_mov_b64_e32 v[20:21], 0
	v_mov_b64_e32 v[22:23], 0
	v_mov_b64_e32 v[24:25], 0
	v_mov_b64_e32 v[26:27], 0
	v_mov_b64_e32 v[28:29], 0
	v_mov_b64_e32 v[30:31], 0
	v_mov_b64_e32 v[32:33], 0
	v_mov_b64_e32 v[34:35], 0
	v_mov_b64_e32 v[36:37], 0
	v_mov_b64_e32 v[38:39], 0
	v_mov_b64_e32 v[40:41], 0
	v_mov_b64_e32 v[42:43], 0
	v_mov_b64_e32 v[44:45], 0
	v_mov_b64_e32 v[46:47], 0
	v_mov_b64_e32 v[48:49], 0
	v_mov_b64_e32 v[50:51], 0
	v_mov_b64_e32 v[52:53], 0
	v_mov_b64_e32 v[54:55], 0
	v_mov_b64_e32 v[56:57], 0
	v_mov_b64_e32 v[58:59], 0
	v_mov_b64_e32 v[60:61], 0
	v_mov_b64_e32 v[62:63], 0
	v_mov_b64_e32 v[64:65], 0
	v_mov_b64_e32 v[66:67], 0
	v_mov_b64_e32 v[68:69], 0
	v_mov_b64_e32 v[70:71], 0
	v_mov_b64_e32 v[72:73], 0
	v_mov_b64_e32 v[74:75], 0
	v_mov_b64_e32 v[76:77], 0
	v_mov_b64_e32 v[78:79], 0
	v_mov_b64_e32 v[80:81], 0
	v_mov_b64_e32 v[82:83], 0
	v_mov_b64_e32 v[84:85], 0
	v_mov_b64_e32 v[86:87], 0
	v_mov_b64_e32 v[88:89], 0
	v_mov_b64_e32 v[90:91], 0
	v_mov_b64_e32 v[92:93], 0
	v_mov_b64_e32 v[94:95], 0
	v_mov_b64_e32 v[96:97], 0
	v_mov_b64_e32 v[98:99], 0
	v_mov_b64_e32 v[100:101], 0
	v_mov_b64_e32 v[102:103], 0
	v_mov_b64_e32 v[104:105], 0
	v_mov_b64_e32 v[106:107], 0
	v_mov_b64_e32 v[108:109], 0
	v_mov_b64_e32 v[110:111], 0
	v_mov_b64_e32 v[112:113], 0
	v_mov_b64_e32 v[114:115], 0
	v_mov_b64_e32 v[116:117], 0
	v_mov_b64_e32 v[118:119], 0
	v_mov_b64_e32 v[120:121], 0
	v_mov_b64_e32 v[122:123], 0
	v_mov_b64_e32 v[124:125], 0
	v_mov_b64_e32 v[126:127], 0
